# natten epilogue: second query-half gate loads issued together with the first half's at the epilogue top (into spare registers), dropping the second exposed load latency per task
# speedup vs baseline: 1.0076x; 1.0007x over previous
; __device__ __forceinline__ bf16_t f2bf(float f) { unsigned u = __float_as_uint(f); u += 0x7FFFu + ((u >> 16) & 1u); return (bf16_t)(u >> 16); }
; __device__ __forceinline__ float bperm_f(int addr, float v) { return __uint_as_float((unsigned)__builtin_amdgcn_ds_bpermute(addr, (int)__float_as_uint(v))); }
; __device__ __forceinline__ float silu(float x) { return x * __builtin_amdgcn_rcpf(1.0f + __expf(-x)); }
; __device__ __forceinline__ void attn_store_out(const f32x16& o0, const f32x16& o1, float inv, const bf16_t* __restrict__ gbase, int qt, bf16_t* __restrict__ yout, int b, int h, int hh) {
;     uint2 gws[2][4];
; #pragma unroll
;     for (int dt = 0; dt < 2; ++dt)
; #pragma unroll
;         for (int g = 0; g < 4; ++g) gws[dt][g] = *(const uint2*)(gbase + qt * 64 + dt * 32 + 8 * g + 4 * hh);
; #pragma unroll
;     for (int dt = 0; dt < 2; ++dt)
; #pragma unroll
;         for (int g = 0; g < 4; ++g) { const int d0 = dt * 32 + 8 * g + 4 * hh;
;             const uint2 gw = gws[dt][g];
;             const float g0 = __uint_as_float(gw.x << 16), g1 = __uint_as_float(gw.x & 0xffff0000u), g2 = __uint_as_float(gw.y << 16), g3 = __uint_as_float(gw.y & 0xffff0000u);
;             const float v0 = (dt ? o1[4 * g] : o0[4 * g]) * inv, v1 = (dt ? o1[4 * g + 1] : o0[4 * g + 1]) * inv, v2 = (dt ? o1[4 * g + 2] : o0[4 * g + 2]) * inv, v3 = (dt ? o1[4 * g + 3] : o0[4 * g + 3]) * inv;
;             uint2 w; w.x = (unsigned)f2bf(v0 * silu(g0)) | ((unsigned)f2bf(v1 * silu(g1)) << 16); w.y = (unsigned)f2bf(v2 * silu(g2)) | ((unsigned)f2bf(v3 * silu(g3)) << 16);
;             *(uint2*)(yout + (size_t)(b * SEQ + qt) * 1024 + h * 64 + d0) = w; }
; }
; __device__ __forceinline__ void natten_wave_task2(const bf16_t* __restrict__ proj, int b, int h, NatPol pA, NatPol pB, bf16_t* __restrict__ yout, int lane, LAS unsigned char* wl) {
;     ...
;     lA += bperm_f(xaddr, lA); lB += bperm_f(xaddr, lB);
;     attn_store_out(oA0, oA1, 1.0f / lA, gbase, qtA, yout, b, h, hh);
.LBB0_375:
	ds_bpermute_b32 v64, v180, v174
	s_add_u32 s6, s6, 0xc000000
	s_addc_u32 s7, s7, 0
	v_mov_b32_e32 v165, v193
	ds_bpermute_b32 v65, v180, v175
	s_waitcnt lgkmcnt(1)
	v_add_f32_e32 v64, v174, v64
	v_div_scale_f32 v66, s[10:11], v64, v64, 1.0
	v_rcp_f32_e32 v67, v66
	s_waitcnt lgkmcnt(0)
	v_add_f32_e32 v65, v175, v65
	v_mov_b32_e32 v87, v50
	v_mov_b32_e32 v50, v49
	v_fma_f32 v68, -v66, v67, 1.0
	v_fmac_f32_e32 v67, v68, v67
	v_div_scale_f32 v68, vcc, 1.0, v64, 1.0
	v_mul_f32_e32 v69, v68, v67
	v_fma_f32 v70, -v66, v69, v68
	v_fmac_f32_e32 v69, v70, v67
	v_fma_f32 v66, -v66, v69, v68
	v_div_fmas_f32 v66, v66, v67, v69
	v_div_fixup_f32 v64, v66, v64, 1.0
	v_lshl_add_u64 v[66:67], v[168:169], 1, s[6:7]
	v_lshl_add_u64 v[66:67], v[66:67], 0, v[164:165]
	global_load_dwordx2 v[80:81], v[66:67], off
	global_load_dwordx2 v[82:83], v[66:67], off offset:16
	global_load_dwordx2 v[78:79], v[66:67], off offset:32
	global_load_dwordx2 v[76:77], v[66:67], off offset:48
	global_load_dwordx2 v[74:75], v[66:67], off offset:64
	global_load_dwordx2 v[72:73], v[66:67], off offset:80
	global_load_dwordx2 v[70:71], v[66:67], off offset:96
	global_load_dwordx2 v[68:69], v[66:67], off offset:112
	v_lshl_add_u64 v[90:91], v[166:167], 1, s[6:7]
	v_lshl_add_u64 v[90:91], v[90:91], 0, v[164:165]
	global_load_dwordx2 v[92:93], v[90:91], off
	global_load_dwordx2 v[94:95], v[90:91], off offset:16
	global_load_dwordx2 v[96:97], v[90:91], off offset:32
	global_load_dwordx2 v[98:99], v[90:91], off offset:48
	global_load_dwordx2 v[100:101], v[90:91], off offset:64
	global_load_dwordx2 v[102:103], v[90:91], off offset:80
	global_load_dwordx2 v[104:105], v[90:91], off offset:96
	global_load_dwordx2 v[106:107], v[90:91], off offset:112
	v_mov_b32_e32 v86, v48
	v_pk_mul_f32 v[48:49], v[50:51], v[64:65] op_sel_hi:[1,0]
	v_pk_mul_f32 v[86:87], v[86:87], v[64:65] op_sel_hi:[1,0]
	s_lshl_b32 s10, s1, 12
	v_add_u32_e32 v66, s10, v205
	v_ashrrev_i32_e32 v67, 31, v66
	v_readlane_b32 s14, v252, 40
	v_lshlrev_b64 v[66:67], 11, v[66:67]
	v_readlane_b32 s15, v252, 41
	s_lshl_b32 s62, s0, 7
	s_waitcnt vmcnt(15)
	v_lshlrev_b32_e32 v84, 16, v80
	v_and_b32_e32 v80, 0xffff0000, v80
	v_mul_f32_e32 v51, 0xbfb8aa3b, v80
	v_exp_f32_e32 v51, v51
	v_lshlrev_b32_e32 v85, 16, v81
	v_mul_f32_e32 v50, 0xbfb8aa3b, v84
	v_exp_f32_e32 v50, v50
	v_add_f32_e32 v51, 1.0, v51
	v_rcp_f32_e32 v88, v51
	v_mul_f32_e32 v51, 0xbfb8aa3b, v85
	v_exp_f32_e32 v51, v51
	v_add_f32_e32 v50, 1.0, v50
	v_rcp_f32_e32 v50, v50
	v_and_b32_e32 v81, 0xffff0000, v81
	v_add_f32_e32 v51, 1.0, v51
	v_rcp_f32_e32 v51, v51
	v_lshl_add_u64 v[66:67], s[14:15], 0, v[66:67]
	v_lshl_add_u64 v[66:67], v[66:67], 0, s[62:63]
	v_lshl_add_u64 v[66:67], v[66:67], 0, v[164:165]
	v_pk_mul_f32 v[50:51], v[50:51], v[84:85]
	s_nop 0
	v_pk_mul_f32 v[50:51], v[86:87], v[50:51]
	s_nop 0
	v_and_b32_sdwa v85, v50, v229 dst_sel:DWORD dst_unused:UNUSED_PAD src0_sel:WORD_1 src1_sel:DWORD
	v_add3_u32 v85, v50, v85, s33
	v_mul_f32_e32 v50, 0xbfb8aa3b, v81
	v_exp_f32_e32 v50, v50
	v_and_b32_sdwa v84, v51, v229 dst_sel:DWORD dst_unused:UNUSED_PAD src0_sel:WORD_1 src1_sel:DWORD
	v_add3_u32 v84, v51, v84, s33
	v_add_f32_e32 v50, 1.0, v50
	v_rcp_f32_e32 v89, v50
	s_nop 0
	v_pk_mul_f32 v[50:51], v[88:89], v[80:81]
	s_nop 0
	v_pk_mul_f32 v[48:49], v[48:49], v[50:51]
	v_mov_b32_e32 v81, v54
	v_and_b32_sdwa v50, v49, v229 dst_sel:DWORD dst_unused:UNUSED_PAD src0_sel:WORD_1 src1_sel:DWORD
	v_and_b32_sdwa v51, v48, v229 dst_sel:DWORD dst_unused:UNUSED_PAD src0_sel:WORD_1 src1_sel:DWORD
	v_add3_u32 v49, v49, v50, s33
	v_add3_u32 v48, v48, v51, s33
	v_and_b32_e32 v49, 0xffff0000, v49
	v_and_b32_e32 v48, 0xffff0000, v48
	v_or_b32_sdwa v49, v49, v84 dst_sel:DWORD dst_unused:UNUSED_PAD src0_sel:DWORD src1_sel:WORD_1
	v_or_b32_sdwa v48, v48, v85 dst_sel:DWORD dst_unused:UNUSED_PAD src0_sel:DWORD src1_sel:WORD_1
	global_store_dwordx2 v[66:67], v[48:49], off
	s_waitcnt vmcnt(15)
	v_and_b32_e32 v48, 0xffff0000, v82
	v_mov_b32_e32 v54, v53
	v_mov_b32_e32 v80, v52
	v_pk_mul_f32 v[52:53], v[54:55], v[64:65] op_sel_hi:[1,0]
	v_mul_f32_e32 v55, 0xbfb8aa3b, v48
	v_exp_f32_e32 v55, v55
	v_lshlrev_b32_e32 v51, 16, v83
	v_lshlrev_b32_e32 v50, 16, v82
	v_mul_f32_e32 v54, 0xbfb8aa3b, v50
	v_add_f32_e32 v55, 1.0, v55
	v_rcp_f32_e32 v82, v55
	v_mul_f32_e32 v55, 0xbfb8aa3b, v51
	v_exp_f32_e32 v54, v54
	v_exp_f32_e32 v55, v55
	v_pk_mul_f32 v[80:81], v[80:81], v[64:65] op_sel_hi:[1,0]
	v_and_b32_e32 v49, 0xffff0000, v83
	v_add_f32_e32 v54, 1.0, v54
	v_add_f32_e32 v55, 1.0, v55
	v_rcp_f32_e32 v54, v54
	v_rcp_f32_e32 v55, v55
	s_nop 0
	v_pk_mul_f32 v[50:51], v[54:55], v[50:51]
	s_nop 0
	v_pk_mul_f32 v[50:51], v[80:81], v[50:51]
	s_nop 0
	v_and_b32_sdwa v54, v51, v229 dst_sel:DWORD dst_unused:UNUSED_PAD src0_sel:WORD_1 src1_sel:DWORD
	v_add3_u32 v51, v51, v54, s33
	v_mul_f32_e32 v54, 0xbfb8aa3b, v49
	v_exp_f32_e32 v54, v54
	v_and_b32_sdwa v55, v50, v229 dst_sel:DWORD dst_unused:UNUSED_PAD src0_sel:WORD_1 src1_sel:DWORD
	v_add3_u32 v50, v50, v55, s33
	v_add_f32_e32 v54, 1.0, v54
	v_rcp_f32_e32 v83, v54
	s_nop 0
	v_pk_mul_f32 v[48:49], v[82:83], v[48:49]
	s_nop 0
	v_pk_mul_f32 v[48:49], v[52:53], v[48:49]
	s_nop 0
	v_and_b32_sdwa v53, v48, v229 dst_sel:DWORD dst_unused:UNUSED_PAD src0_sel:WORD_1 src1_sel:DWORD
	v_add3_u32 v48, v48, v53, s33
	v_and_b32_e32 v48, 0xffff0000, v48
	v_or_b32_sdwa v48, v48, v50 dst_sel:DWORD dst_unused:UNUSED_PAD src0_sel:DWORD src1_sel:WORD_1
	s_waitcnt vmcnt(14)
; __device__ __forceinline__ bf16_t f2bf(float f) { unsigned u = __float_as_uint(f); u += 0x7FFFu + ((u >> 16) & 1u); return (bf16_t)(u >> 16); }
; __device__ __forceinline__ float silu(float x) { return x * __builtin_amdgcn_rcpf(1.0f + __expf(-x)); }
; __device__ __forceinline__ void attn_store_out(const f32x16& o0, const f32x16& o1, float inv, const bf16_t* __restrict__ gbase, int qt, bf16_t* __restrict__ yout, int b, int h, int hh) {
;     uint2 gws[2][4];
; #pragma unroll
;     for (int dt = 0; dt < 2; ++dt)
; #pragma unroll
;         for (int g = 0; g < 4; ++g) gws[dt][g] = *(const uint2*)(gbase + qt * 64 + dt * 32 + 8 * g + 4 * hh);
; #pragma unroll
;     for (int dt = 0; dt < 2; ++dt)
; #pragma unroll
;         for (int g = 0; g < 4; ++g) { const int d0 = dt * 32 + 8 * g + 4 * hh;
;             const uint2 gw = gws[dt][g];
;             const float g0 = __uint_as_float(gw.x << 16), g1 = __uint_as_float(gw.x & 0xffff0000u), g2 = __uint_as_float(gw.y << 16), g3 = __uint_as_float(gw.y & 0xffff0000u);
;             const float v0 = (dt ? o1[4 * g] : o0[4 * g]) * inv, v1 = (dt ? o1[4 * g + 1] : o0[4 * g + 1]) * inv, v2 = (dt ? o1[4 * g + 2] : o0[4 * g + 2]) * inv, v3 = (dt ? o1[4 * g + 3] : o0[4 * g + 3]) * inv;
;             uint2 w; w.x = (unsigned)f2bf(v0 * silu(g0)) | ((unsigned)f2bf(v1 * silu(g1)) << 16); w.y = (unsigned)f2bf(v2 * silu(g2)) | ((unsigned)f2bf(v3 * silu(g3)) << 16);
;             *(uint2*)(yout + (size_t)(b * SEQ + qt) * 1024 + h * 64 + d0) = w; }
; }
	v_and_b32_e32 v50, 0xffff0000, v78
	v_mov_b32_e32 v53, v58
	v_mov_b32_e32 v58, v57
	v_mul_f32_e32 v57, 0xbfb8aa3b, v50
	v_and_b32_sdwa v52, v49, v229 dst_sel:DWORD dst_unused:UNUSED_PAD src0_sel:WORD_1 src1_sel:DWORD
	v_exp_f32_e32 v57, v57
	v_add3_u32 v49, v49, v52, s33
	v_and_b32_e32 v49, 0xffff0000, v49
	v_or_b32_sdwa v49, v49, v51 dst_sel:DWORD dst_unused:UNUSED_PAD src0_sel:DWORD src1_sel:WORD_1
	global_store_dwordx2 v[66:67], v[48:49], off offset:16
	v_lshlrev_b32_e32 v49, 16, v79
	v_lshlrev_b32_e32 v48, 16, v78
	v_add_f32_e32 v57, 1.0, v57
	v_mov_b32_e32 v52, v56
	v_pk_mul_f32 v[54:55], v[58:59], v[64:65] op_sel_hi:[1,0]
	v_mul_f32_e32 v56, 0xbfb8aa3b, v48
	v_rcp_f32_e32 v58, v57
	v_mul_f32_e32 v57, 0xbfb8aa3b, v49
	v_exp_f32_e32 v56, v56
	v_exp_f32_e32 v57, v57
	v_pk_mul_f32 v[52:53], v[52:53], v[64:65] op_sel_hi:[1,0]
	v_and_b32_e32 v51, 0xffff0000, v79
	v_add_f32_e32 v56, 1.0, v56
	v_add_f32_e32 v57, 1.0, v57
	v_rcp_f32_e32 v56, v56
	v_rcp_f32_e32 v57, v57
	s_nop 0
	v_pk_mul_f32 v[48:49], v[56:57], v[48:49]
	s_nop 0
	v_pk_mul_f32 v[48:49], v[52:53], v[48:49]
	s_nop 0
	v_and_b32_sdwa v53, v48, v229 dst_sel:DWORD dst_unused:UNUSED_PAD src0_sel:WORD_1 src1_sel:DWORD
	v_add3_u32 v53, v48, v53, s33
	v_mul_f32_e32 v48, 0xbfb8aa3b, v51
	v_exp_f32_e32 v48, v48
	v_and_b32_sdwa v52, v49, v229 dst_sel:DWORD dst_unused:UNUSED_PAD src0_sel:WORD_1 src1_sel:DWORD
	v_add3_u32 v52, v49, v52, s33
	v_add_f32_e32 v48, 1.0, v48
	v_rcp_f32_e32 v59, v48
	s_nop 0
	v_pk_mul_f32 v[48:49], v[58:59], v[50:51]
	s_nop 0
	v_pk_mul_f32 v[48:49], v[54:55], v[48:49]
	s_nop 0
	v_and_b32_sdwa v50, v49, v229 dst_sel:DWORD dst_unused:UNUSED_PAD src0_sel:WORD_1 src1_sel:DWORD
	v_add3_u32 v49, v49, v50, s33
	s_waitcnt vmcnt(14)
	v_and_b32_e32 v50, 0xffff0000, v76
	v_mul_f32_e32 v57, 0xbfb8aa3b, v50
	v_and_b32_sdwa v51, v48, v229 dst_sel:DWORD dst_unused:UNUSED_PAD src0_sel:WORD_1 src1_sel:DWORD
	v_exp_f32_e32 v57, v57
	v_add3_u32 v48, v48, v51, s33
	v_and_b32_e32 v49, 0xffff0000, v49
	v_and_b32_e32 v48, 0xffff0000, v48
	v_or_b32_sdwa v49, v49, v52 dst_sel:DWORD dst_unused:UNUSED_PAD src0_sel:DWORD src1_sel:WORD_1
	v_or_b32_sdwa v48, v48, v53 dst_sel:DWORD dst_unused:UNUSED_PAD src0_sel:DWORD src1_sel:WORD_1
	global_store_dwordx2 v[66:67], v[48:49], off offset:32
	v_lshlrev_b32_e32 v49, 16, v77
	v_lshlrev_b32_e32 v48, 16, v76
	v_add_f32_e32 v57, 1.0, v57
	v_mul_f32_e32 v56, 0xbfb8aa3b, v48
	v_rcp_f32_e32 v58, v57
	v_mul_f32_e32 v57, 0xbfb8aa3b, v49
	v_exp_f32_e32 v56, v56
	v_exp_f32_e32 v57, v57
	v_mov_b32_e32 v52, v60
	v_mov_b32_e32 v53, v62
	v_add_f32_e32 v56, 1.0, v56
	v_add_f32_e32 v57, 1.0, v57
	v_rcp_f32_e32 v56, v56
	v_rcp_f32_e32 v57, v57
	v_pk_mul_f32 v[52:53], v[52:53], v[64:65] op_sel_hi:[1,0]
	v_and_b32_e32 v51, 0xffff0000, v77
	v_mov_b32_e32 v62, v61
	v_pk_mul_f32 v[48:49], v[56:57], v[48:49]
	v_pk_mul_f32 v[54:55], v[62:63], v[64:65] op_sel_hi:[1,0]
	v_pk_mul_f32 v[48:49], v[52:53], v[48:49]
	s_nop 0
	v_and_b32_sdwa v53, v48, v229 dst_sel:DWORD dst_unused:UNUSED_PAD src0_sel:WORD_1 src1_sel:DWORD
	v_add3_u32 v53, v48, v53, s33
	v_mul_f32_e32 v48, 0xbfb8aa3b, v51
	v_exp_f32_e32 v48, v48
	v_and_b32_sdwa v52, v49, v229 dst_sel:DWORD dst_unused:UNUSED_PAD src0_sel:WORD_1 src1_sel:DWORD
	v_add3_u32 v52, v49, v52, s33
	v_add_f32_e32 v48, 1.0, v48
	v_rcp_f32_e32 v59, v48
	s_nop 0
	v_pk_mul_f32 v[48:49], v[58:59], v[50:51]
	s_nop 0
	v_pk_mul_f32 v[48:49], v[54:55], v[48:49]
	s_nop 0
	v_and_b32_sdwa v51, v48, v229 dst_sel:DWORD dst_unused:UNUSED_PAD src0_sel:WORD_1 src1_sel:DWORD
	v_and_b32_sdwa v50, v49, v229 dst_sel:DWORD dst_unused:UNUSED_PAD src0_sel:WORD_1 src1_sel:DWORD
	v_add3_u32 v48, v48, v51, s33
	v_add3_u32 v49, v49, v50, s33
	v_and_b32_e32 v48, 0xffff0000, v48
	v_and_b32_e32 v49, 0xffff0000, v49
	v_or_b32_sdwa v48, v48, v53 dst_sel:DWORD dst_unused:UNUSED_PAD src0_sel:DWORD src1_sel:WORD_1
	s_waitcnt vmcnt(14)
	v_and_b32_e32 v50, 0xffff0000, v74
	v_mov_b32_e32 v53, v34
	v_mov_b32_e32 v34, v33
	v_or_b32_sdwa v49, v49, v52 dst_sel:DWORD dst_unused:UNUSED_PAD src0_sel:DWORD src1_sel:WORD_1
	v_mov_b32_e32 v52, v32
	v_pk_mul_f32 v[32:33], v[34:35], v[64:65] op_sel_hi:[1,0]
	v_mul_f32_e32 v35, 0xbfb8aa3b, v50
	v_exp_f32_e32 v35, v35
	global_store_dwordx2 v[66:67], v[48:49], off offset:48
	v_lshlrev_b32_e32 v49, 16, v75
	v_lshlrev_b32_e32 v48, 16, v74
	v_add_f32_e32 v35, 1.0, v35
	v_mul_f32_e32 v34, 0xbfb8aa3b, v48
	v_rcp_f32_e32 v54, v35
	v_mul_f32_e32 v35, 0xbfb8aa3b, v49
	v_exp_f32_e32 v34, v34
	v_exp_f32_e32 v35, v35
	v_pk_mul_f32 v[52:53], v[52:53], v[64:65] op_sel_hi:[1,0]
	v_and_b32_e32 v51, 0xffff0000, v75
	v_add_f32_e32 v34, 1.0, v34
	v_add_f32_e32 v35, 1.0, v35
	v_rcp_f32_e32 v34, v34
	v_rcp_f32_e32 v35, v35
	s_nop 0
	v_pk_mul_f32 v[34:35], v[34:35], v[48:49]
	s_nop 0
	v_pk_mul_f32 v[34:35], v[52:53], v[34:35]
	s_nop 0
	v_and_b32_sdwa v49, v34, v229 dst_sel:DWORD dst_unused:UNUSED_PAD src0_sel:WORD_1 src1_sel:DWORD
	v_add3_u32 v49, v34, v49, s33
	v_mul_f32_e32 v34, 0xbfb8aa3b, v51
	v_exp_f32_e32 v34, v34
	v_and_b32_sdwa v48, v35, v229 dst_sel:DWORD dst_unused:UNUSED_PAD src0_sel:WORD_1 src1_sel:DWORD
	v_add3_u32 v48, v35, v48, s33
	v_add_f32_e32 v34, 1.0, v34
	v_rcp_f32_e32 v55, v34
	s_nop 0
	v_pk_mul_f32 v[34:35], v[54:55], v[50:51]
	s_nop 0
	v_pk_mul_f32 v[32:33], v[32:33], v[34:35]
	v_mov_b32_e32 v55, v18
	v_and_b32_sdwa v35, v32, v229 dst_sel:DWORD dst_unused:UNUSED_PAD src0_sel:WORD_1 src1_sel:DWORD
	v_and_b32_sdwa v34, v33, v229 dst_sel:DWORD dst_unused:UNUSED_PAD src0_sel:WORD_1 src1_sel:DWORD
	v_add3_u32 v32, v32, v35, s33
	v_add3_u32 v33, v33, v34, s33
	v_and_b32_e32 v32, 0xffff0000, v32
	v_and_b32_e32 v33, 0xffff0000, v33
	v_or_b32_sdwa v32, v32, v49 dst_sel:DWORD dst_unused:UNUSED_PAD src0_sel:DWORD src1_sel:WORD_1
	s_waitcnt vmcnt(14)
; __device__ __forceinline__ bf16_t f2bf(float f) { unsigned u = __float_as_uint(f); u += 0x7FFFu + ((u >> 16) & 1u); return (bf16_t)(u >> 16); }
; __device__ __forceinline__ float bperm_f(int addr, float v) { return __uint_as_float((unsigned)__builtin_amdgcn_ds_bpermute(addr, (int)__float_as_uint(v))); }
; __device__ __forceinline__ float silu(float x) { return x * __builtin_amdgcn_rcpf(1.0f + __expf(-x)); }
; __device__ __forceinline__ void attn_store_out(const f32x16& o0, const f32x16& o1, float inv, const bf16_t* __restrict__ gbase, int qt, bf16_t* __restrict__ yout, int b, int h, int hh) {
;     uint2 gws[2][4];
; #pragma unroll
;     for (int dt = 0; dt < 2; ++dt)
; #pragma unroll
;         for (int g = 0; g < 4; ++g) gws[dt][g] = *(const uint2*)(gbase + qt * 64 + dt * 32 + 8 * g + 4 * hh);
; #pragma unroll
;     for (int dt = 0; dt < 2; ++dt)
; #pragma unroll
;         for (int g = 0; g < 4; ++g) { const int d0 = dt * 32 + 8 * g + 4 * hh;
;             const uint2 gw = gws[dt][g];
;             const float g0 = __uint_as_float(gw.x << 16), g1 = __uint_as_float(gw.x & 0xffff0000u), g2 = __uint_as_float(gw.y << 16), g3 = __uint_as_float(gw.y & 0xffff0000u);
;             const float v0 = (dt ? o1[4 * g] : o0[4 * g]) * inv, v1 = (dt ? o1[4 * g + 1] : o0[4 * g + 1]) * inv, v2 = (dt ? o1[4 * g + 2] : o0[4 * g + 2]) * inv, v3 = (dt ? o1[4 * g + 3] : o0[4 * g + 3]) * inv;
;             uint2 w; w.x = (unsigned)f2bf(v0 * silu(g0)) | ((unsigned)f2bf(v1 * silu(g1)) << 16); w.y = (unsigned)f2bf(v2 * silu(g2)) | ((unsigned)f2bf(v3 * silu(g3)) << 16);
;             *(uint2*)(yout + (size_t)(b * SEQ + qt) * 1024 + h * 64 + d0) = w; }
; }
; __device__ __forceinline__ void natten_wave_task2(const bf16_t* __restrict__ proj, int b, int h, NatPol pA, NatPol pB, bf16_t* __restrict__ yout, int lane, LAS unsigned char* wl) {
;     ...
;     lA += bperm_f(xaddr, lA); lB += bperm_f(xaddr, lB);
;     attn_store_out(oA0, oA1, 1.0f / lA, gbase, qtA, yout, b, h, hh);
;     attn_store_out(oB0, oB1, 1.0f / lB, gbase, qtB, yout, b, h, hh);
	v_and_b32_e32 v34, 0xffff0000, v72
	v_mov_b32_e32 v49, v38
	v_mov_b32_e32 v38, v37
	v_or_b32_sdwa v33, v33, v48 dst_sel:DWORD dst_unused:UNUSED_PAD src0_sel:DWORD src1_sel:WORD_1
	v_mov_b32_e32 v48, v36
	v_pk_mul_f32 v[36:37], v[38:39], v[64:65] op_sel_hi:[1,0]
	v_mul_f32_e32 v39, 0xbfb8aa3b, v34
	v_exp_f32_e32 v39, v39
	global_store_dwordx2 v[66:67], v[32:33], off offset:64
	v_lshlrev_b32_e32 v33, 16, v73
	v_lshlrev_b32_e32 v32, 16, v72
	v_add_f32_e32 v39, 1.0, v39
	v_mul_f32_e32 v38, 0xbfb8aa3b, v32
	v_rcp_f32_e32 v50, v39
	v_mul_f32_e32 v39, 0xbfb8aa3b, v33
	v_exp_f32_e32 v38, v38
	v_exp_f32_e32 v39, v39
	v_pk_mul_f32 v[48:49], v[48:49], v[64:65] op_sel_hi:[1,0]
	v_and_b32_e32 v35, 0xffff0000, v73
	v_add_f32_e32 v38, 1.0, v38
	v_add_f32_e32 v39, 1.0, v39
	v_rcp_f32_e32 v38, v38
	v_rcp_f32_e32 v39, v39
	v_mov_b32_e32 v18, v17
	v_mov_b32_e32 v54, v16
	v_pk_mul_f32 v[32:33], v[38:39], v[32:33]
	s_nop 0
	v_pk_mul_f32 v[32:33], v[48:49], v[32:33]
	s_nop 0
	v_and_b32_sdwa v39, v32, v229 dst_sel:DWORD dst_unused:UNUSED_PAD src0_sel:WORD_1 src1_sel:DWORD
	v_add3_u32 v39, v32, v39, s33
	v_mul_f32_e32 v32, 0xbfb8aa3b, v35
	v_exp_f32_e32 v32, v32
	v_and_b32_sdwa v38, v33, v229 dst_sel:DWORD dst_unused:UNUSED_PAD src0_sel:WORD_1 src1_sel:DWORD
	v_add3_u32 v38, v33, v38, s33
	v_add_f32_e32 v32, 1.0, v32
	v_rcp_f32_e32 v51, v32
	s_nop 0
	v_pk_mul_f32 v[32:33], v[50:51], v[34:35]
	s_nop 0
	v_pk_mul_f32 v[32:33], v[36:37], v[32:33]
	v_mov_b32_e32 v37, v42
	v_and_b32_sdwa v34, v33, v229 dst_sel:DWORD dst_unused:UNUSED_PAD src0_sel:WORD_1 src1_sel:DWORD
	v_add3_u32 v33, v33, v34, s33
	s_waitcnt vmcnt(14)
	v_and_b32_e32 v34, 0xffff0000, v70
	v_mov_b32_e32 v42, v41
	v_mul_f32_e32 v41, 0xbfb8aa3b, v34
	v_and_b32_sdwa v35, v32, v229 dst_sel:DWORD dst_unused:UNUSED_PAD src0_sel:WORD_1 src1_sel:DWORD
	v_exp_f32_e32 v41, v41
	v_add3_u32 v32, v32, v35, s33
	v_and_b32_e32 v33, 0xffff0000, v33
	v_and_b32_e32 v32, 0xffff0000, v32
	v_or_b32_sdwa v33, v33, v38 dst_sel:DWORD dst_unused:UNUSED_PAD src0_sel:DWORD src1_sel:WORD_1
	v_or_b32_sdwa v32, v32, v39 dst_sel:DWORD dst_unused:UNUSED_PAD src0_sel:DWORD src1_sel:WORD_1
	global_store_dwordx2 v[66:67], v[32:33], off offset:80
	v_lshlrev_b32_e32 v33, 16, v71
	v_lshlrev_b32_e32 v32, 16, v70
	v_add_f32_e32 v41, 1.0, v41
	v_mov_b32_e32 v36, v40
	v_pk_mul_f32 v[38:39], v[42:43], v[64:65] op_sel_hi:[1,0]
	v_mul_f32_e32 v40, 0xbfb8aa3b, v32
	v_rcp_f32_e32 v42, v41
	v_mul_f32_e32 v41, 0xbfb8aa3b, v33
	v_exp_f32_e32 v40, v40
	v_exp_f32_e32 v41, v41
	v_pk_mul_f32 v[36:37], v[36:37], v[64:65] op_sel_hi:[1,0]
	v_and_b32_e32 v35, 0xffff0000, v71
	v_add_f32_e32 v40, 1.0, v40
	v_add_f32_e32 v41, 1.0, v41
	v_rcp_f32_e32 v40, v40
	v_rcp_f32_e32 v41, v41
	s_nop 0
	v_pk_mul_f32 v[32:33], v[40:41], v[32:33]
	s_nop 0
	v_pk_mul_f32 v[32:33], v[36:37], v[32:33]
	s_nop 0
	v_and_b32_sdwa v37, v32, v229 dst_sel:DWORD dst_unused:UNUSED_PAD src0_sel:WORD_1 src1_sel:DWORD
	v_add3_u32 v37, v32, v37, s33
	v_mul_f32_e32 v32, 0xbfb8aa3b, v35
	v_exp_f32_e32 v32, v32
	v_and_b32_sdwa v36, v33, v229 dst_sel:DWORD dst_unused:UNUSED_PAD src0_sel:WORD_1 src1_sel:DWORD
	v_add3_u32 v36, v33, v36, s33
	v_add_f32_e32 v32, 1.0, v32
	v_rcp_f32_e32 v43, v32
	s_nop 0
	v_pk_mul_f32 v[32:33], v[42:43], v[34:35]
	s_nop 0
	v_pk_mul_f32 v[32:33], v[38:39], v[32:33]
	s_nop 0
	v_and_b32_sdwa v34, v33, v229 dst_sel:DWORD dst_unused:UNUSED_PAD src0_sel:WORD_1 src1_sel:DWORD
	v_add3_u32 v33, v33, v34, s33
	s_waitcnt vmcnt(14)
	v_and_b32_e32 v34, 0xffff0000, v68
	v_mul_f32_e32 v41, 0xbfb8aa3b, v34
	v_exp_f32_e32 v41, v41
	v_and_b32_sdwa v35, v32, v229 dst_sel:DWORD dst_unused:UNUSED_PAD src0_sel:WORD_1 src1_sel:DWORD
	v_add3_u32 v32, v32, v35, s33
	v_and_b32_e32 v33, 0xffff0000, v33
	v_and_b32_e32 v32, 0xffff0000, v32
	v_or_b32_sdwa v33, v33, v36 dst_sel:DWORD dst_unused:UNUSED_PAD src0_sel:DWORD src1_sel:WORD_1
	v_or_b32_sdwa v32, v32, v37 dst_sel:DWORD dst_unused:UNUSED_PAD src0_sel:DWORD src1_sel:WORD_1
	v_lshlrev_b32_e32 v37, 16, v69
	v_lshlrev_b32_e32 v36, 16, v68
	v_add_f32_e32 v41, 1.0, v41
	v_mul_f32_e32 v40, 0xbfb8aa3b, v36
	v_rcp_f32_e32 v42, v41
	v_mul_f32_e32 v41, 0xbfb8aa3b, v37
	v_exp_f32_e32 v40, v40
	v_exp_f32_e32 v41, v41
	global_store_dwordx2 v[66:67], v[32:33], off offset:96
	v_mov_b32_e32 v32, v44
	v_add_f32_e32 v40, 1.0, v40
	v_add_f32_e32 v41, 1.0, v41
	v_rcp_f32_e32 v40, v40
	v_rcp_f32_e32 v41, v41
	v_mov_b32_e32 v33, v46
	v_pk_mul_f32 v[32:33], v[32:33], v[64:65] op_sel_hi:[1,0]
	v_and_b32_e32 v35, 0xffff0000, v69
	v_pk_mul_f32 v[36:37], v[40:41], v[36:37]
	v_mov_b32_e32 v46, v45
	v_pk_mul_f32 v[32:33], v[32:33], v[36:37]
	v_pk_mul_f32 v[38:39], v[46:47], v[64:65] op_sel_hi:[1,0]
	v_and_b32_sdwa v37, v32, v229 dst_sel:DWORD dst_unused:UNUSED_PAD src0_sel:WORD_1 src1_sel:DWORD
	v_add3_u32 v37, v32, v37, s33
	v_mul_f32_e32 v32, 0xbfb8aa3b, v35
	v_exp_f32_e32 v32, v32
	v_and_b32_sdwa v36, v33, v229 dst_sel:DWORD dst_unused:UNUSED_PAD src0_sel:WORD_1 src1_sel:DWORD
	v_add3_u32 v36, v33, v36, s33
	v_add_f32_e32 v32, 1.0, v32
	v_rcp_f32_e32 v43, v32
	s_nop 0
	v_pk_mul_f32 v[32:33], v[42:43], v[34:35]
	s_nop 0
	v_pk_mul_f32 v[32:33], v[38:39], v[32:33]
	s_nop 0
	v_and_b32_sdwa v34, v33, v229 dst_sel:DWORD dst_unused:UNUSED_PAD src0_sel:WORD_1 src1_sel:DWORD
	v_and_b32_sdwa v35, v32, v229 dst_sel:DWORD dst_unused:UNUSED_PAD src0_sel:WORD_1 src1_sel:DWORD
	v_add3_u32 v33, v33, v34, s33
	v_add3_u32 v32, v32, v35, s33
	v_and_b32_e32 v33, 0xffff0000, v33
	v_and_b32_e32 v32, 0xffff0000, v32
	v_or_b32_sdwa v33, v33, v36 dst_sel:DWORD dst_unused:UNUSED_PAD src0_sel:DWORD src1_sel:WORD_1
	v_or_b32_sdwa v32, v32, v37 dst_sel:DWORD dst_unused:UNUSED_PAD src0_sel:DWORD src1_sel:WORD_1
	global_store_dwordx2 v[66:67], v[32:33], off offset:112
	v_div_scale_f32 v32, s[0:1], v65, v65, 1.0
	v_rcp_f32_e32 v33, v32
	v_readlane_b32 s0, v252, 53
	s_add_i32 s52, s52, s0
	s_cmpk_gt_i32 s52, 0x1fff
	v_fma_f32 v34, -v32, v33, 1.0
	v_fmac_f32_e32 v33, v34, v33
	v_div_scale_f32 v34, vcc, 1.0, v65, 1.0
	v_mul_f32_e32 v35, v34, v33
	v_fma_f32 v36, -v32, v35, v34
	v_fmac_f32_e32 v35, v36, v33
	v_fma_f32 v32, -v32, v35, v34
	v_div_fmas_f32 v32, v32, v33, v35
	v_lshl_add_u64 v[34:35], v[166:167], 1, s[6:7]
	v_lshl_add_u64 v[34:35], v[34:35], 0, v[164:165]
	s_waitcnt vmcnt(8)
; __device__ __forceinline__ bf16_t f2bf(float f) { unsigned u = __float_as_uint(f); u += 0x7FFFu + ((u >> 16) & 1u); return (bf16_t)(u >> 16); }
; __device__ __forceinline__ float silu(float x) { return x * __builtin_amdgcn_rcpf(1.0f + __expf(-x)); }
; __device__ __forceinline__ void attn_store_out(const f32x16& o0, const f32x16& o1, float inv, const bf16_t* __restrict__ gbase, int qt, bf16_t* __restrict__ yout, int b, int h, int hh) {
;     uint2 gws[2][4];
; #pragma unroll
;     for (int dt = 0; dt < 2; ++dt)
; #pragma unroll
;         for (int g = 0; g < 4; ++g) gws[dt][g] = *(const uint2*)(gbase + qt * 64 + dt * 32 + 8 * g + 4 * hh);
; #pragma unroll
;     for (int dt = 0; dt < 2; ++dt)
; #pragma unroll
;         for (int g = 0; g < 4; ++g) { const int d0 = dt * 32 + 8 * g + 4 * hh;
;             const uint2 gw = gws[dt][g];
;             const float g0 = __uint_as_float(gw.x << 16), g1 = __uint_as_float(gw.x & 0xffff0000u), g2 = __uint_as_float(gw.y << 16), g3 = __uint_as_float(gw.y & 0xffff0000u);
;             const float v0 = (dt ? o1[4 * g] : o0[4 * g]) * inv, v1 = (dt ? o1[4 * g + 1] : o0[4 * g + 1]) * inv, v2 = (dt ? o1[4 * g + 2] : o0[4 * g + 2]) * inv, v3 = (dt ? o1[4 * g + 3] : o0[4 * g + 3]) * inv;
;             uint2 w; w.x = (unsigned)f2bf(v0 * silu(g0)) | ((unsigned)f2bf(v1 * silu(g1)) << 16); w.y = (unsigned)f2bf(v2 * silu(g2)) | ((unsigned)f2bf(v3 * silu(g3)) << 16);
;             *(uint2*)(yout + (size_t)(b * SEQ + qt) * 1024 + h * 64 + d0) = w; }
; }
	v_mov_b32_e32 v48, v92
	v_mov_b32_e32 v49, v93
	v_mov_b32_e32 v50, v94
	v_mov_b32_e32 v51, v95
	v_mov_b32_e32 v46, v96
	v_mov_b32_e32 v47, v97
	v_mov_b32_e32 v44, v98
	v_mov_b32_e32 v45, v99
	v_mov_b32_e32 v42, v100
	v_mov_b32_e32 v43, v101
	v_mov_b32_e32 v40, v102
	v_mov_b32_e32 v41, v103
	v_mov_b32_e32 v38, v104
	v_mov_b32_e32 v39, v105
	v_mov_b32_e32 v36, v106
	v_mov_b32_e32 v37, v107
	v_div_fixup_f32 v32, v32, v65, 1.0
	v_pk_mul_f32 v[16:17], v[18:19], v[32:33] op_sel_hi:[1,0]
	v_pk_mul_f32 v[54:55], v[54:55], v[32:33] op_sel_hi:[1,0]
	v_add_u32_e32 v34, s10, v204
	v_ashrrev_i32_e32 v35, 31, v34
	v_lshlrev_b64 v[34:35], 11, v[34:35]
	v_lshl_add_u64 v[34:35], s[14:15], 0, v[34:35]
	v_lshl_add_u64 v[34:35], v[34:35], 0, s[62:63]
	v_lshl_add_u64 v[34:35], v[34:35], 0, v[164:165]
	v_lshlrev_b32_e32 v52, 16, v48
	v_and_b32_e32 v48, 0xffff0000, v48
	v_mul_f32_e32 v19, 0xbfb8aa3b, v48
	v_exp_f32_e32 v19, v19
	v_lshlrev_b32_e32 v53, 16, v49
	v_mul_f32_e32 v18, 0xbfb8aa3b, v52
	v_exp_f32_e32 v18, v18
	v_add_f32_e32 v19, 1.0, v19
	v_rcp_f32_e32 v56, v19
	v_mul_f32_e32 v19, 0xbfb8aa3b, v53
	v_exp_f32_e32 v19, v19
	v_add_f32_e32 v18, 1.0, v18
	v_rcp_f32_e32 v18, v18
	v_and_b32_e32 v49, 0xffff0000, v49
	v_add_f32_e32 v19, 1.0, v19
	v_rcp_f32_e32 v19, v19
	s_nop 0
	v_pk_mul_f32 v[18:19], v[18:19], v[52:53]
	s_nop 0
	v_pk_mul_f32 v[18:19], v[54:55], v[18:19]
	s_nop 0
	v_and_b32_sdwa v52, v18, v229 dst_sel:DWORD dst_unused:UNUSED_PAD src0_sel:WORD_1 src1_sel:DWORD
	v_add3_u32 v52, v18, v52, s33
	v_mul_f32_e32 v18, 0xbfb8aa3b, v49
	v_exp_f32_e32 v18, v18
	v_and_b32_sdwa v33, v19, v229 dst_sel:DWORD dst_unused:UNUSED_PAD src0_sel:WORD_1 src1_sel:DWORD
	v_add3_u32 v33, v19, v33, s33
	v_add_f32_e32 v18, 1.0, v18
	v_rcp_f32_e32 v57, v18
	s_nop 0
	v_pk_mul_f32 v[18:19], v[56:57], v[48:49]
	s_nop 0
	v_pk_mul_f32 v[16:17], v[16:17], v[18:19]
	v_mov_b32_e32 v49, v22
	v_and_b32_sdwa v18, v17, v229 dst_sel:DWORD dst_unused:UNUSED_PAD src0_sel:WORD_1 src1_sel:DWORD
	v_add3_u32 v17, v17, v18, s33
	v_and_b32_e32 v18, 0xffff0000, v50
	v_mov_b32_e32 v22, v21
	v_mov_b32_e32 v48, v20
	v_pk_mul_f32 v[20:21], v[22:23], v[32:33] op_sel_hi:[1,0]
	v_mul_f32_e32 v23, 0xbfb8aa3b, v18
	v_and_b32_sdwa v19, v16, v229 dst_sel:DWORD dst_unused:UNUSED_PAD src0_sel:WORD_1 src1_sel:DWORD
	v_exp_f32_e32 v23, v23
	v_add3_u32 v16, v16, v19, s33
	v_and_b32_e32 v17, 0xffff0000, v17
	v_and_b32_e32 v16, 0xffff0000, v16
	v_or_b32_sdwa v17, v17, v33 dst_sel:DWORD dst_unused:UNUSED_PAD src0_sel:DWORD src1_sel:WORD_1
	v_or_b32_sdwa v16, v16, v52 dst_sel:DWORD dst_unused:UNUSED_PAD src0_sel:DWORD src1_sel:WORD_1
	global_store_dwordx2 v[34:35], v[16:17], off
	v_lshlrev_b32_e32 v17, 16, v51
	v_lshlrev_b32_e32 v16, 16, v50
	v_add_f32_e32 v23, 1.0, v23
	v_mul_f32_e32 v22, 0xbfb8aa3b, v16
	v_rcp_f32_e32 v50, v23
	v_mul_f32_e32 v23, 0xbfb8aa3b, v17
	v_exp_f32_e32 v22, v22
	v_exp_f32_e32 v23, v23
	v_pk_mul_f32 v[48:49], v[48:49], v[32:33] op_sel_hi:[1,0]
	v_and_b32_e32 v19, 0xffff0000, v51
	v_add_f32_e32 v22, 1.0, v22
	v_add_f32_e32 v23, 1.0, v23
	v_rcp_f32_e32 v22, v22
	v_rcp_f32_e32 v23, v23
	s_nop 0
	v_pk_mul_f32 v[16:17], v[22:23], v[16:17]
	s_nop 0
	v_pk_mul_f32 v[16:17], v[48:49], v[16:17]
	s_nop 0
	v_and_b32_sdwa v23, v16, v229 dst_sel:DWORD dst_unused:UNUSED_PAD src0_sel:WORD_1 src1_sel:DWORD
	v_add3_u32 v23, v16, v23, s33
	v_mul_f32_e32 v16, 0xbfb8aa3b, v19
	v_exp_f32_e32 v16, v16
	v_and_b32_sdwa v22, v17, v229 dst_sel:DWORD dst_unused:UNUSED_PAD src0_sel:WORD_1 src1_sel:DWORD
	v_add3_u32 v22, v17, v22, s33
	v_add_f32_e32 v16, 1.0, v16
	v_rcp_f32_e32 v51, v16
	s_nop 0
	v_pk_mul_f32 v[16:17], v[50:51], v[18:19]
	s_nop 0
	v_pk_mul_f32 v[16:17], v[20:21], v[16:17]
	v_mov_b32_e32 v21, v26
	v_and_b32_sdwa v18, v17, v229 dst_sel:DWORD dst_unused:UNUSED_PAD src0_sel:WORD_1 src1_sel:DWORD
	v_add3_u32 v17, v17, v18, s33
	v_and_b32_e32 v18, 0xffff0000, v46
	v_mov_b32_e32 v26, v25
	v_mul_f32_e32 v25, 0xbfb8aa3b, v18
	v_and_b32_sdwa v19, v16, v229 dst_sel:DWORD dst_unused:UNUSED_PAD src0_sel:WORD_1 src1_sel:DWORD
	v_exp_f32_e32 v25, v25
	v_add3_u32 v16, v16, v19, s33
	v_and_b32_e32 v17, 0xffff0000, v17
	v_and_b32_e32 v16, 0xffff0000, v16
	v_or_b32_sdwa v17, v17, v22 dst_sel:DWORD dst_unused:UNUSED_PAD src0_sel:DWORD src1_sel:WORD_1
	v_or_b32_sdwa v16, v16, v23 dst_sel:DWORD dst_unused:UNUSED_PAD src0_sel:DWORD src1_sel:WORD_1
	global_store_dwordx2 v[34:35], v[16:17], off offset:16
	v_lshlrev_b32_e32 v17, 16, v47
	v_lshlrev_b32_e32 v16, 16, v46
	v_add_f32_e32 v25, 1.0, v25
	v_mov_b32_e32 v20, v24
	v_pk_mul_f32 v[22:23], v[26:27], v[32:33] op_sel_hi:[1,0]
	v_mul_f32_e32 v24, 0xbfb8aa3b, v16
	v_rcp_f32_e32 v26, v25
	v_mul_f32_e32 v25, 0xbfb8aa3b, v17
	v_exp_f32_e32 v24, v24
	v_exp_f32_e32 v25, v25
	v_pk_mul_f32 v[20:21], v[20:21], v[32:33] op_sel_hi:[1,0]
	v_and_b32_e32 v19, 0xffff0000, v47
	v_add_f32_e32 v24, 1.0, v24
	v_add_f32_e32 v25, 1.0, v25
	v_rcp_f32_e32 v24, v24
	v_rcp_f32_e32 v25, v25
	s_nop 0
	v_pk_mul_f32 v[16:17], v[24:25], v[16:17]
	s_nop 0
	v_pk_mul_f32 v[16:17], v[20:21], v[16:17]
	s_nop 0
	v_and_b32_sdwa v21, v16, v229 dst_sel:DWORD dst_unused:UNUSED_PAD src0_sel:WORD_1 src1_sel:DWORD
	v_add3_u32 v21, v16, v21, s33
	v_mul_f32_e32 v16, 0xbfb8aa3b, v19
	v_exp_f32_e32 v16, v16
	v_and_b32_sdwa v20, v17, v229 dst_sel:DWORD dst_unused:UNUSED_PAD src0_sel:WORD_1 src1_sel:DWORD
	v_add3_u32 v20, v17, v20, s33
	v_add_f32_e32 v16, 1.0, v16
	v_rcp_f32_e32 v27, v16
	s_nop 0
	v_pk_mul_f32 v[16:17], v[26:27], v[18:19]
	s_nop 0
	v_pk_mul_f32 v[16:17], v[22:23], v[16:17]
	s_nop 0
	v_and_b32_sdwa v18, v17, v229 dst_sel:DWORD dst_unused:UNUSED_PAD src0_sel:WORD_1 src1_sel:DWORD
	v_add3_u32 v17, v17, v18, s33
; __device__ __forceinline__ bf16_t f2bf(float f) { unsigned u = __float_as_uint(f); u += 0x7FFFu + ((u >> 16) & 1u); return (bf16_t)(u >> 16); }
; __device__ __forceinline__ float silu(float x) { return x * __builtin_amdgcn_rcpf(1.0f + __expf(-x)); }
; __device__ __forceinline__ void attn_store_out(const f32x16& o0, const f32x16& o1, float inv, const bf16_t* __restrict__ gbase, int qt, bf16_t* __restrict__ yout, int b, int h, int hh) {
;     uint2 gws[2][4];
; #pragma unroll
;     for (int dt = 0; dt < 2; ++dt)
; #pragma unroll
;         for (int g = 0; g < 4; ++g) gws[dt][g] = *(const uint2*)(gbase + qt * 64 + dt * 32 + 8 * g + 4 * hh);
; #pragma unroll
;     for (int dt = 0; dt < 2; ++dt)
; #pragma unroll
;         for (int g = 0; g < 4; ++g) { const int d0 = dt * 32 + 8 * g + 4 * hh;
;             const uint2 gw = gws[dt][g];
;             const float g0 = __uint_as_float(gw.x << 16), g1 = __uint_as_float(gw.x & 0xffff0000u), g2 = __uint_as_float(gw.y << 16), g3 = __uint_as_float(gw.y & 0xffff0000u);
;             const float v0 = (dt ? o1[4 * g] : o0[4 * g]) * inv, v1 = (dt ? o1[4 * g + 1] : o0[4 * g + 1]) * inv, v2 = (dt ? o1[4 * g + 2] : o0[4 * g + 2]) * inv, v3 = (dt ? o1[4 * g + 3] : o0[4 * g + 3]) * inv;
;             uint2 w; w.x = (unsigned)f2bf(v0 * silu(g0)) | ((unsigned)f2bf(v1 * silu(g1)) << 16); w.y = (unsigned)f2bf(v2 * silu(g2)) | ((unsigned)f2bf(v3 * silu(g3)) << 16);
;             *(uint2*)(yout + (size_t)(b * SEQ + qt) * 1024 + h * 64 + d0) = w; }
; }
	v_and_b32_e32 v18, 0xffff0000, v44
	v_mul_f32_e32 v25, 0xbfb8aa3b, v18
	v_and_b32_sdwa v19, v16, v229 dst_sel:DWORD dst_unused:UNUSED_PAD src0_sel:WORD_1 src1_sel:DWORD
	v_exp_f32_e32 v25, v25
	v_add3_u32 v16, v16, v19, s33
	v_and_b32_e32 v17, 0xffff0000, v17
	v_and_b32_e32 v16, 0xffff0000, v16
	v_or_b32_sdwa v17, v17, v20 dst_sel:DWORD dst_unused:UNUSED_PAD src0_sel:DWORD src1_sel:WORD_1
	v_or_b32_sdwa v16, v16, v21 dst_sel:DWORD dst_unused:UNUSED_PAD src0_sel:DWORD src1_sel:WORD_1
	global_store_dwordx2 v[34:35], v[16:17], off offset:32
	v_lshlrev_b32_e32 v17, 16, v45
	v_lshlrev_b32_e32 v16, 16, v44
	v_add_f32_e32 v25, 1.0, v25
	v_mul_f32_e32 v24, 0xbfb8aa3b, v16
	v_rcp_f32_e32 v26, v25
	v_mul_f32_e32 v25, 0xbfb8aa3b, v17
	v_exp_f32_e32 v24, v24
	v_exp_f32_e32 v25, v25
	v_mov_b32_e32 v20, v28
	v_mov_b32_e32 v21, v30
	v_add_f32_e32 v24, 1.0, v24
	v_add_f32_e32 v25, 1.0, v25
	v_rcp_f32_e32 v24, v24
	v_rcp_f32_e32 v25, v25
	v_pk_mul_f32 v[20:21], v[20:21], v[32:33] op_sel_hi:[1,0]
	v_and_b32_e32 v19, 0xffff0000, v45
	v_mov_b32_e32 v30, v29
	v_pk_mul_f32 v[16:17], v[24:25], v[16:17]
	v_pk_mul_f32 v[22:23], v[30:31], v[32:33] op_sel_hi:[1,0]
	v_pk_mul_f32 v[16:17], v[20:21], v[16:17]
	s_nop 0
	v_and_b32_sdwa v21, v16, v229 dst_sel:DWORD dst_unused:UNUSED_PAD src0_sel:WORD_1 src1_sel:DWORD
	v_add3_u32 v21, v16, v21, s33
	v_mul_f32_e32 v16, 0xbfb8aa3b, v19
	v_exp_f32_e32 v16, v16
	v_and_b32_sdwa v20, v17, v229 dst_sel:DWORD dst_unused:UNUSED_PAD src0_sel:WORD_1 src1_sel:DWORD
	v_add3_u32 v20, v17, v20, s33
	v_add_f32_e32 v16, 1.0, v16
	v_rcp_f32_e32 v27, v16
	s_nop 0
	v_pk_mul_f32 v[16:17], v[26:27], v[18:19]
	s_nop 0
	v_pk_mul_f32 v[16:17], v[22:23], v[16:17]
	s_nop 0
	v_and_b32_sdwa v19, v16, v229 dst_sel:DWORD dst_unused:UNUSED_PAD src0_sel:WORD_1 src1_sel:DWORD
	v_and_b32_sdwa v18, v17, v229 dst_sel:DWORD dst_unused:UNUSED_PAD src0_sel:WORD_1 src1_sel:DWORD
	v_add3_u32 v16, v16, v19, s33
	v_add3_u32 v17, v17, v18, s33
	v_and_b32_e32 v16, 0xffff0000, v16
	v_and_b32_e32 v17, 0xffff0000, v17
	v_or_b32_sdwa v16, v16, v21 dst_sel:DWORD dst_unused:UNUSED_PAD src0_sel:DWORD src1_sel:WORD_1
	v_and_b32_e32 v18, 0xffff0000, v42
	v_mov_b32_e32 v21, v2
	v_mov_b32_e32 v2, v1
	v_or_b32_sdwa v17, v17, v20 dst_sel:DWORD dst_unused:UNUSED_PAD src0_sel:DWORD src1_sel:WORD_1
	v_mov_b32_e32 v20, v0
	v_pk_mul_f32 v[0:1], v[2:3], v[32:33] op_sel_hi:[1,0]
	v_mul_f32_e32 v3, 0xbfb8aa3b, v18
	v_exp_f32_e32 v3, v3
	global_store_dwordx2 v[34:35], v[16:17], off offset:48
	v_lshlrev_b32_e32 v17, 16, v43
	v_lshlrev_b32_e32 v16, 16, v42
	v_add_f32_e32 v3, 1.0, v3
	v_mul_f32_e32 v2, 0xbfb8aa3b, v16
	v_rcp_f32_e32 v22, v3
	v_mul_f32_e32 v3, 0xbfb8aa3b, v17
	v_exp_f32_e32 v2, v2
	v_exp_f32_e32 v3, v3
	v_pk_mul_f32 v[20:21], v[20:21], v[32:33] op_sel_hi:[1,0]
	v_and_b32_e32 v19, 0xffff0000, v43
	v_add_f32_e32 v2, 1.0, v2
	v_add_f32_e32 v3, 1.0, v3
	v_rcp_f32_e32 v2, v2
	v_rcp_f32_e32 v3, v3
	s_nop 0
	v_pk_mul_f32 v[2:3], v[2:3], v[16:17]
	s_nop 0
	v_pk_mul_f32 v[2:3], v[20:21], v[2:3]
	s_nop 0
	v_and_b32_sdwa v17, v2, v229 dst_sel:DWORD dst_unused:UNUSED_PAD src0_sel:WORD_1 src1_sel:DWORD
	v_add3_u32 v17, v2, v17, s33
	v_mul_f32_e32 v2, 0xbfb8aa3b, v19
	v_exp_f32_e32 v2, v2
	v_and_b32_sdwa v16, v3, v229 dst_sel:DWORD dst_unused:UNUSED_PAD src0_sel:WORD_1 src1_sel:DWORD
	v_add3_u32 v16, v3, v16, s33
	v_add_f32_e32 v2, 1.0, v2
	v_rcp_f32_e32 v23, v2
	s_nop 0
	v_pk_mul_f32 v[2:3], v[22:23], v[18:19]
	s_nop 0
	v_pk_mul_f32 v[0:1], v[0:1], v[2:3]
	s_nop 0
	v_and_b32_sdwa v3, v0, v229 dst_sel:DWORD dst_unused:UNUSED_PAD src0_sel:WORD_1 src1_sel:DWORD
	v_and_b32_sdwa v2, v1, v229 dst_sel:DWORD dst_unused:UNUSED_PAD src0_sel:WORD_1 src1_sel:DWORD
	v_add3_u32 v0, v0, v3, s33
	v_add3_u32 v1, v1, v2, s33
	v_and_b32_e32 v0, 0xffff0000, v0
	v_and_b32_e32 v1, 0xffff0000, v1
	v_or_b32_sdwa v0, v0, v17 dst_sel:DWORD dst_unused:UNUSED_PAD src0_sel:DWORD src1_sel:WORD_1
	v_and_b32_e32 v2, 0xffff0000, v40
	v_mov_b32_e32 v17, v6
	v_mov_b32_e32 v6, v5
	v_or_b32_sdwa v1, v1, v16 dst_sel:DWORD dst_unused:UNUSED_PAD src0_sel:DWORD src1_sel:WORD_1
	v_mov_b32_e32 v16, v4
	v_pk_mul_f32 v[4:5], v[6:7], v[32:33] op_sel_hi:[1,0]
	v_mul_f32_e32 v7, 0xbfb8aa3b, v2
	v_exp_f32_e32 v7, v7
	global_store_dwordx2 v[34:35], v[0:1], off offset:64
	v_lshlrev_b32_e32 v1, 16, v41
	v_lshlrev_b32_e32 v0, 16, v40
	v_add_f32_e32 v7, 1.0, v7
	v_mul_f32_e32 v6, 0xbfb8aa3b, v0
	v_rcp_f32_e32 v18, v7
	v_mul_f32_e32 v7, 0xbfb8aa3b, v1
	v_exp_f32_e32 v6, v6
	v_exp_f32_e32 v7, v7
	v_pk_mul_f32 v[16:17], v[16:17], v[32:33] op_sel_hi:[1,0]
	v_and_b32_e32 v3, 0xffff0000, v41
	v_add_f32_e32 v6, 1.0, v6
	v_add_f32_e32 v7, 1.0, v7
; __device__ __forceinline__ bf16_t f2bf(float f) { unsigned u = __float_as_uint(f); u += 0x7FFFu + ((u >> 16) & 1u); return (bf16_t)(u >> 16); }
; __device__ __forceinline__ float silu(float x) { return x * __builtin_amdgcn_rcpf(1.0f + __expf(-x)); }
; __device__ __forceinline__ void attn_store_out(const f32x16& o0, const f32x16& o1, float inv, const bf16_t* __restrict__ gbase, int qt, bf16_t* __restrict__ yout, int b, int h, int hh) {
;     uint2 gws[2][4];
; #pragma unroll
;     for (int dt = 0; dt < 2; ++dt)
; #pragma unroll
;         for (int g = 0; g < 4; ++g) gws[dt][g] = *(const uint2*)(gbase + qt * 64 + dt * 32 + 8 * g + 4 * hh);
; #pragma unroll
;     for (int dt = 0; dt < 2; ++dt)
; #pragma unroll
;         for (int g = 0; g < 4; ++g) { const int d0 = dt * 32 + 8 * g + 4 * hh;
;             const uint2 gw = gws[dt][g];
;             const float g0 = __uint_as_float(gw.x << 16), g1 = __uint_as_float(gw.x & 0xffff0000u), g2 = __uint_as_float(gw.y << 16), g3 = __uint_as_float(gw.y & 0xffff0000u);
;             const float v0 = (dt ? o1[4 * g] : o0[4 * g]) * inv, v1 = (dt ? o1[4 * g + 1] : o0[4 * g + 1]) * inv, v2 = (dt ? o1[4 * g + 2] : o0[4 * g + 2]) * inv, v3 = (dt ? o1[4 * g + 3] : o0[4 * g + 3]) * inv;
;             uint2 w; w.x = (unsigned)f2bf(v0 * silu(g0)) | ((unsigned)f2bf(v1 * silu(g1)) << 16); w.y = (unsigned)f2bf(v2 * silu(g2)) | ((unsigned)f2bf(v3 * silu(g3)) << 16);
;             *(uint2*)(yout + (size_t)(b * SEQ + qt) * 1024 + h * 64 + d0) = w; }
; }
	v_rcp_f32_e32 v6, v6
	v_rcp_f32_e32 v7, v7
	s_nop 0
	v_pk_mul_f32 v[0:1], v[6:7], v[0:1]
	s_nop 0
	v_pk_mul_f32 v[0:1], v[16:17], v[0:1]
	s_nop 0
	v_and_b32_sdwa v7, v0, v229 dst_sel:DWORD dst_unused:UNUSED_PAD src0_sel:WORD_1 src1_sel:DWORD
	v_add3_u32 v7, v0, v7, s33
	v_mul_f32_e32 v0, 0xbfb8aa3b, v3
	v_exp_f32_e32 v0, v0
	v_and_b32_sdwa v6, v1, v229 dst_sel:DWORD dst_unused:UNUSED_PAD src0_sel:WORD_1 src1_sel:DWORD
	v_add3_u32 v6, v1, v6, s33
	v_add_f32_e32 v0, 1.0, v0
	v_rcp_f32_e32 v19, v0
	s_nop 0
	v_pk_mul_f32 v[0:1], v[18:19], v[2:3]
	s_nop 0
	v_pk_mul_f32 v[0:1], v[4:5], v[0:1]
	v_mov_b32_e32 v5, v10
	v_and_b32_sdwa v2, v1, v229 dst_sel:DWORD dst_unused:UNUSED_PAD src0_sel:WORD_1 src1_sel:DWORD
	v_add3_u32 v1, v1, v2, s33
	v_and_b32_e32 v2, 0xffff0000, v38
	v_mov_b32_e32 v10, v9
	v_mul_f32_e32 v9, 0xbfb8aa3b, v2
	v_and_b32_sdwa v3, v0, v229 dst_sel:DWORD dst_unused:UNUSED_PAD src0_sel:WORD_1 src1_sel:DWORD
	v_exp_f32_e32 v9, v9
	v_add3_u32 v0, v0, v3, s33
	v_and_b32_e32 v1, 0xffff0000, v1
	v_and_b32_e32 v0, 0xffff0000, v0
	v_or_b32_sdwa v1, v1, v6 dst_sel:DWORD dst_unused:UNUSED_PAD src0_sel:DWORD src1_sel:WORD_1
	v_or_b32_sdwa v0, v0, v7 dst_sel:DWORD dst_unused:UNUSED_PAD src0_sel:DWORD src1_sel:WORD_1
	global_store_dwordx2 v[34:35], v[0:1], off offset:80
	v_lshlrev_b32_e32 v1, 16, v39
	v_lshlrev_b32_e32 v0, 16, v38
	v_add_f32_e32 v9, 1.0, v9
	v_mov_b32_e32 v4, v8
	v_pk_mul_f32 v[6:7], v[10:11], v[32:33] op_sel_hi:[1,0]
	v_mul_f32_e32 v8, 0xbfb8aa3b, v0
	v_rcp_f32_e32 v10, v9
	v_mul_f32_e32 v9, 0xbfb8aa3b, v1
	v_exp_f32_e32 v8, v8
	v_exp_f32_e32 v9, v9
	v_pk_mul_f32 v[4:5], v[4:5], v[32:33] op_sel_hi:[1,0]
	v_and_b32_e32 v3, 0xffff0000, v39
	v_add_f32_e32 v8, 1.0, v8
	v_add_f32_e32 v9, 1.0, v9
	v_rcp_f32_e32 v8, v8
	v_rcp_f32_e32 v9, v9
	s_nop 0
	v_pk_mul_f32 v[0:1], v[8:9], v[0:1]
	s_nop 0
	v_pk_mul_f32 v[0:1], v[4:5], v[0:1]
	s_nop 0
	v_and_b32_sdwa v5, v0, v229 dst_sel:DWORD dst_unused:UNUSED_PAD src0_sel:WORD_1 src1_sel:DWORD
	v_add3_u32 v5, v0, v5, s33
	v_mul_f32_e32 v0, 0xbfb8aa3b, v3
	v_exp_f32_e32 v0, v0
	v_and_b32_sdwa v4, v1, v229 dst_sel:DWORD dst_unused:UNUSED_PAD src0_sel:WORD_1 src1_sel:DWORD
	v_add3_u32 v4, v1, v4, s33
	v_add_f32_e32 v0, 1.0, v0
	v_rcp_f32_e32 v11, v0
	s_nop 0
	v_pk_mul_f32 v[0:1], v[10:11], v[2:3]
	s_nop 0
	v_pk_mul_f32 v[0:1], v[6:7], v[0:1]
	s_nop 0
	v_and_b32_sdwa v2, v1, v229 dst_sel:DWORD dst_unused:UNUSED_PAD src0_sel:WORD_1 src1_sel:DWORD
	v_add3_u32 v1, v1, v2, s33
	v_and_b32_e32 v2, 0xffff0000, v36
	v_mul_f32_e32 v9, 0xbfb8aa3b, v2
	v_exp_f32_e32 v9, v9
	v_and_b32_sdwa v3, v0, v229 dst_sel:DWORD dst_unused:UNUSED_PAD src0_sel:WORD_1 src1_sel:DWORD
	v_add3_u32 v0, v0, v3, s33
	v_and_b32_e32 v1, 0xffff0000, v1
	v_and_b32_e32 v0, 0xffff0000, v0
	v_or_b32_sdwa v1, v1, v4 dst_sel:DWORD dst_unused:UNUSED_PAD src0_sel:DWORD src1_sel:WORD_1
	v_or_b32_sdwa v0, v0, v5 dst_sel:DWORD dst_unused:UNUSED_PAD src0_sel:DWORD src1_sel:WORD_1
	v_lshlrev_b32_e32 v5, 16, v37
	v_lshlrev_b32_e32 v4, 16, v36
	v_add_f32_e32 v9, 1.0, v9
	v_mul_f32_e32 v8, 0xbfb8aa3b, v4
	v_rcp_f32_e32 v10, v9
	v_mul_f32_e32 v9, 0xbfb8aa3b, v5
	v_exp_f32_e32 v8, v8
	v_exp_f32_e32 v9, v9
	global_store_dwordx2 v[34:35], v[0:1], off offset:96
	v_mov_b32_e32 v0, v12
	v_add_f32_e32 v8, 1.0, v8
	v_add_f32_e32 v9, 1.0, v9
	v_rcp_f32_e32 v8, v8
	v_rcp_f32_e32 v9, v9
	v_mov_b32_e32 v1, v14
	v_pk_mul_f32 v[0:1], v[0:1], v[32:33] op_sel_hi:[1,0]
	v_and_b32_e32 v3, 0xffff0000, v37
	v_pk_mul_f32 v[4:5], v[8:9], v[4:5]
	v_mov_b32_e32 v14, v13
	v_pk_mul_f32 v[0:1], v[0:1], v[4:5]
	v_pk_mul_f32 v[6:7], v[14:15], v[32:33] op_sel_hi:[1,0]
	v_and_b32_sdwa v5, v0, v229 dst_sel:DWORD dst_unused:UNUSED_PAD src0_sel:WORD_1 src1_sel:DWORD
	v_add3_u32 v5, v0, v5, s33
	v_mul_f32_e32 v0, 0xbfb8aa3b, v3
	v_exp_f32_e32 v0, v0
	v_and_b32_sdwa v4, v1, v229 dst_sel:DWORD dst_unused:UNUSED_PAD src0_sel:WORD_1 src1_sel:DWORD
	v_add3_u32 v4, v1, v4, s33
	v_add_f32_e32 v0, 1.0, v0
	v_rcp_f32_e32 v11, v0
	s_nop 0
	v_pk_mul_f32 v[0:1], v[10:11], v[2:3]
	s_nop 0
	v_pk_mul_f32 v[0:1], v[6:7], v[0:1]
	s_nop 0
	v_and_b32_sdwa v2, v1, v229 dst_sel:DWORD dst_unused:UNUSED_PAD src0_sel:WORD_1 src1_sel:DWORD
	v_and_b32_sdwa v3, v0, v229 dst_sel:DWORD dst_unused:UNUSED_PAD src0_sel:WORD_1 src1_sel:DWORD
	v_add3_u32 v1, v1, v2, s33
	v_add3_u32 v0, v0, v3, s33
	v_and_b32_e32 v1, 0xffff0000, v1
	v_and_b32_e32 v0, 0xffff0000, v0
	v_or_b32_sdwa v1, v1, v4 dst_sel:DWORD dst_unused:UNUSED_PAD src0_sel:DWORD src1_sel:WORD_1
	v_or_b32_sdwa v0, v0, v5 dst_sel:DWORD dst_unused:UNUSED_PAD src0_sel:DWORD src1_sel:WORD_1
	global_store_dwordx2 v[34:35], v[0:1], off offset:112
	s_cbranch_scc1 .LBB0_390

; __device__ __forceinline__ bf16_t f2bf(float f) { unsigned u = __float_as_uint(f); u += 0x7FFFu + ((u >> 16) & 1u); return (bf16_t)(u >> 16); }
; __device__ __forceinline__ float bperm_f(int addr, float v) { return __uint_as_float((unsigned)__builtin_amdgcn_ds_bpermute(addr, (int)__float_as_uint(v))); }
; __device__ __forceinline__ float silu(float x) { return x * __builtin_amdgcn_rcpf(1.0f + __expf(-x)); }
; __device__ __forceinline__ void attn_store_out(const f32x16& o0, const f32x16& o1, float inv, const bf16_t* __restrict__ gbase, int qt, bf16_t* __restrict__ yout, int b, int h, int hh) {
;     uint2 gws[2][4];
; #pragma unroll
;     for (int dt = 0; dt < 2; ++dt)
; #pragma unroll
;         for (int g = 0; g < 4; ++g) gws[dt][g] = *(const uint2*)(gbase + qt * 64 + dt * 32 + 8 * g + 4 * hh);
; #pragma unroll
;     for (int dt = 0; dt < 2; ++dt)
; #pragma unroll
;         for (int g = 0; g < 4; ++g) { const int d0 = dt * 32 + 8 * g + 4 * hh;
;             const uint2 gw = gws[dt][g];
;             const float g0 = __uint_as_float(gw.x << 16), g1 = __uint_as_float(gw.x & 0xffff0000u), g2 = __uint_as_float(gw.y << 16), g3 = __uint_as_float(gw.y & 0xffff0000u);
;             const float v0 = (dt ? o1[4 * g] : o0[4 * g]) * inv, v1 = (dt ? o1[4 * g + 1] : o0[4 * g + 1]) * inv, v2 = (dt ? o1[4 * g + 2] : o0[4 * g + 2]) * inv, v3 = (dt ? o1[4 * g + 3] : o0[4 * g + 3]) * inv;
;             uint2 w; w.x = (unsigned)f2bf(v0 * silu(g0)) | ((unsigned)f2bf(v1 * silu(g1)) << 16); w.y = (unsigned)f2bf(v2 * silu(g2)) | ((unsigned)f2bf(v3 * silu(g3)) << 16);
;             *(uint2*)(yout + (size_t)(b * SEQ + qt) * 1024 + h * 64 + d0) = w; }
; }
; __device__ __forceinline__ void natten_wave_task2(const bf16_t* __restrict__ proj, int b, int h, NatPol pA, NatPol pB, bf16_t* __restrict__ yout, int lane, LAS unsigned char* wl) {
;     ...
;     lA += bperm_f(xaddr, lA); lB += bperm_f(xaddr, lB);
;     attn_store_out(oA0, oA1, 1.0f / lA, gbase, qtA, yout, b, h, hh);
.LBB0_561:
	ds_bpermute_b32 v64, v180, v174
	s_add_u32 s6, s6, 0xc000000
	s_addc_u32 s7, s7, 0
	v_mov_b32_e32 v165, v193
	ds_bpermute_b32 v65, v180, v175
	s_waitcnt lgkmcnt(1)
	v_add_f32_e32 v64, v174, v64
	v_div_scale_f32 v66, s[10:11], v64, v64, 1.0
	v_rcp_f32_e32 v67, v66
	s_waitcnt lgkmcnt(0)
	v_add_f32_e32 v65, v175, v65
	v_mov_b32_e32 v87, v50
	v_mov_b32_e32 v50, v49
	v_fma_f32 v68, -v66, v67, 1.0
	v_fmac_f32_e32 v67, v68, v67
	v_div_scale_f32 v68, vcc, 1.0, v64, 1.0
	v_mul_f32_e32 v69, v68, v67
	v_fma_f32 v70, -v66, v69, v68
	v_fmac_f32_e32 v69, v70, v67
	v_fma_f32 v66, -v66, v69, v68
	v_div_fmas_f32 v66, v66, v67, v69
	v_div_fixup_f32 v64, v66, v64, 1.0
	v_lshl_add_u64 v[66:67], v[168:169], 1, s[6:7]
	v_lshl_add_u64 v[66:67], v[66:67], 0, v[164:165]
	global_load_dwordx2 v[80:81], v[66:67], off
	global_load_dwordx2 v[82:83], v[66:67], off offset:16
	global_load_dwordx2 v[78:79], v[66:67], off offset:32
	global_load_dwordx2 v[76:77], v[66:67], off offset:48
	global_load_dwordx2 v[74:75], v[66:67], off offset:64
	global_load_dwordx2 v[72:73], v[66:67], off offset:80
	global_load_dwordx2 v[70:71], v[66:67], off offset:96
	global_load_dwordx2 v[68:69], v[66:67], off offset:112
	v_lshl_add_u64 v[90:91], v[166:167], 1, s[6:7]
	v_lshl_add_u64 v[90:91], v[90:91], 0, v[164:165]
	global_load_dwordx2 v[92:93], v[90:91], off
	global_load_dwordx2 v[94:95], v[90:91], off offset:16
	global_load_dwordx2 v[96:97], v[90:91], off offset:32
	global_load_dwordx2 v[98:99], v[90:91], off offset:48
	global_load_dwordx2 v[100:101], v[90:91], off offset:64
	global_load_dwordx2 v[102:103], v[90:91], off offset:80
	global_load_dwordx2 v[104:105], v[90:91], off offset:96
	global_load_dwordx2 v[106:107], v[90:91], off offset:112
	v_mov_b32_e32 v86, v48
	v_pk_mul_f32 v[48:49], v[50:51], v[64:65] op_sel_hi:[1,0]
	v_pk_mul_f32 v[86:87], v[86:87], v[64:65] op_sel_hi:[1,0]
	s_lshl_b32 s10, s1, 12
	v_add_u32_e32 v66, s10, v205
	v_ashrrev_i32_e32 v67, 31, v66
	v_readlane_b32 s14, v254, 17
	v_lshlrev_b64 v[66:67], 11, v[66:67]
	v_readlane_b32 s15, v254, 18
	s_lshl_b32 s62, s0, 7
	s_waitcnt vmcnt(15)
	v_lshlrev_b32_e32 v84, 16, v80
	v_and_b32_e32 v80, 0xffff0000, v80
	v_mul_f32_e32 v51, 0xbfb8aa3b, v80
	v_exp_f32_e32 v51, v51
	v_lshlrev_b32_e32 v85, 16, v81
	v_mul_f32_e32 v50, 0xbfb8aa3b, v84
	v_exp_f32_e32 v50, v50
	v_add_f32_e32 v51, 1.0, v51
	v_rcp_f32_e32 v88, v51
	v_mul_f32_e32 v51, 0xbfb8aa3b, v85
	v_exp_f32_e32 v51, v51
	v_add_f32_e32 v50, 1.0, v50
	v_rcp_f32_e32 v50, v50
	v_and_b32_e32 v81, 0xffff0000, v81
	v_add_f32_e32 v51, 1.0, v51
	v_rcp_f32_e32 v51, v51
	v_lshl_add_u64 v[66:67], s[14:15], 0, v[66:67]
	v_lshl_add_u64 v[66:67], v[66:67], 0, s[62:63]
	v_lshl_add_u64 v[66:67], v[66:67], 0, v[164:165]
	v_pk_mul_f32 v[50:51], v[50:51], v[84:85]
	s_nop 0
	v_pk_mul_f32 v[50:51], v[86:87], v[50:51]
	s_nop 0
	v_and_b32_sdwa v85, v50, v229 dst_sel:DWORD dst_unused:UNUSED_PAD src0_sel:WORD_1 src1_sel:DWORD
	v_add3_u32 v85, v50, v85, s33
	v_mul_f32_e32 v50, 0xbfb8aa3b, v81
	v_exp_f32_e32 v50, v50
	v_and_b32_sdwa v84, v51, v229 dst_sel:DWORD dst_unused:UNUSED_PAD src0_sel:WORD_1 src1_sel:DWORD
	v_add3_u32 v84, v51, v84, s33
	v_add_f32_e32 v50, 1.0, v50
	v_rcp_f32_e32 v89, v50
	s_nop 0
	v_pk_mul_f32 v[50:51], v[88:89], v[80:81]
	s_nop 0
	v_pk_mul_f32 v[48:49], v[48:49], v[50:51]
	v_mov_b32_e32 v81, v54
	v_and_b32_sdwa v50, v49, v229 dst_sel:DWORD dst_unused:UNUSED_PAD src0_sel:WORD_1 src1_sel:DWORD
	v_and_b32_sdwa v51, v48, v229 dst_sel:DWORD dst_unused:UNUSED_PAD src0_sel:WORD_1 src1_sel:DWORD
	v_add3_u32 v49, v49, v50, s33
	v_add3_u32 v48, v48, v51, s33
	v_and_b32_e32 v49, 0xffff0000, v49
	v_and_b32_e32 v48, 0xffff0000, v48
	v_or_b32_sdwa v49, v49, v84 dst_sel:DWORD dst_unused:UNUSED_PAD src0_sel:DWORD src1_sel:WORD_1
	v_or_b32_sdwa v48, v48, v85 dst_sel:DWORD dst_unused:UNUSED_PAD src0_sel:DWORD src1_sel:WORD_1
	global_store_dwordx2 v[66:67], v[48:49], off
	s_waitcnt vmcnt(15)
	v_and_b32_e32 v48, 0xffff0000, v82
	v_mov_b32_e32 v54, v53
	v_mov_b32_e32 v80, v52
	v_pk_mul_f32 v[52:53], v[54:55], v[64:65] op_sel_hi:[1,0]
	v_mul_f32_e32 v55, 0xbfb8aa3b, v48
	v_exp_f32_e32 v55, v55
	v_lshlrev_b32_e32 v51, 16, v83
	v_lshlrev_b32_e32 v50, 16, v82
	v_mul_f32_e32 v54, 0xbfb8aa3b, v50
	v_add_f32_e32 v55, 1.0, v55
	v_rcp_f32_e32 v82, v55
	v_mul_f32_e32 v55, 0xbfb8aa3b, v51
	v_exp_f32_e32 v54, v54
	v_exp_f32_e32 v55, v55
	v_pk_mul_f32 v[80:81], v[80:81], v[64:65] op_sel_hi:[1,0]
	v_and_b32_e32 v49, 0xffff0000, v83
	v_add_f32_e32 v54, 1.0, v54
	v_add_f32_e32 v55, 1.0, v55
	v_rcp_f32_e32 v54, v54
	v_rcp_f32_e32 v55, v55
	s_nop 0
	v_pk_mul_f32 v[50:51], v[54:55], v[50:51]
	s_nop 0
	v_pk_mul_f32 v[50:51], v[80:81], v[50:51]
	s_nop 0
	v_and_b32_sdwa v54, v51, v229 dst_sel:DWORD dst_unused:UNUSED_PAD src0_sel:WORD_1 src1_sel:DWORD
	v_add3_u32 v51, v51, v54, s33
	v_mul_f32_e32 v54, 0xbfb8aa3b, v49
	v_exp_f32_e32 v54, v54
	v_and_b32_sdwa v55, v50, v229 dst_sel:DWORD dst_unused:UNUSED_PAD src0_sel:WORD_1 src1_sel:DWORD
	v_add3_u32 v50, v50, v55, s33
	v_add_f32_e32 v54, 1.0, v54
	v_rcp_f32_e32 v83, v54
	s_nop 0
	v_pk_mul_f32 v[48:49], v[82:83], v[48:49]
	s_nop 0
	v_pk_mul_f32 v[48:49], v[52:53], v[48:49]
	s_nop 0
	v_and_b32_sdwa v53, v48, v229 dst_sel:DWORD dst_unused:UNUSED_PAD src0_sel:WORD_1 src1_sel:DWORD
	v_add3_u32 v48, v48, v53, s33
	v_and_b32_e32 v48, 0xffff0000, v48
	v_or_b32_sdwa v48, v48, v50 dst_sel:DWORD dst_unused:UNUSED_PAD src0_sel:DWORD src1_sel:WORD_1
	s_waitcnt vmcnt(14)
; __device__ __forceinline__ bf16_t f2bf(float f) { unsigned u = __float_as_uint(f); u += 0x7FFFu + ((u >> 16) & 1u); return (bf16_t)(u >> 16); }
; __device__ __forceinline__ float silu(float x) { return x * __builtin_amdgcn_rcpf(1.0f + __expf(-x)); }
; __device__ __forceinline__ void attn_store_out(const f32x16& o0, const f32x16& o1, float inv, const bf16_t* __restrict__ gbase, int qt, bf16_t* __restrict__ yout, int b, int h, int hh) {
;     uint2 gws[2][4];
; #pragma unroll
;     for (int dt = 0; dt < 2; ++dt)
; #pragma unroll
;         for (int g = 0; g < 4; ++g) gws[dt][g] = *(const uint2*)(gbase + qt * 64 + dt * 32 + 8 * g + 4 * hh);
; #pragma unroll
;     for (int dt = 0; dt < 2; ++dt)
; #pragma unroll
;         for (int g = 0; g < 4; ++g) { const int d0 = dt * 32 + 8 * g + 4 * hh;
;             const uint2 gw = gws[dt][g];
;             const float g0 = __uint_as_float(gw.x << 16), g1 = __uint_as_float(gw.x & 0xffff0000u), g2 = __uint_as_float(gw.y << 16), g3 = __uint_as_float(gw.y & 0xffff0000u);
;             const float v0 = (dt ? o1[4 * g] : o0[4 * g]) * inv, v1 = (dt ? o1[4 * g + 1] : o0[4 * g + 1]) * inv, v2 = (dt ? o1[4 * g + 2] : o0[4 * g + 2]) * inv, v3 = (dt ? o1[4 * g + 3] : o0[4 * g + 3]) * inv;
;             uint2 w; w.x = (unsigned)f2bf(v0 * silu(g0)) | ((unsigned)f2bf(v1 * silu(g1)) << 16); w.y = (unsigned)f2bf(v2 * silu(g2)) | ((unsigned)f2bf(v3 * silu(g3)) << 16);
;             *(uint2*)(yout + (size_t)(b * SEQ + qt) * 1024 + h * 64 + d0) = w; }
; }
	v_and_b32_e32 v50, 0xffff0000, v78
	v_mov_b32_e32 v53, v58
	v_mov_b32_e32 v58, v57
	v_mul_f32_e32 v57, 0xbfb8aa3b, v50
	v_and_b32_sdwa v52, v49, v229 dst_sel:DWORD dst_unused:UNUSED_PAD src0_sel:WORD_1 src1_sel:DWORD
	v_exp_f32_e32 v57, v57
	v_add3_u32 v49, v49, v52, s33
	v_and_b32_e32 v49, 0xffff0000, v49
	v_or_b32_sdwa v49, v49, v51 dst_sel:DWORD dst_unused:UNUSED_PAD src0_sel:DWORD src1_sel:WORD_1
	global_store_dwordx2 v[66:67], v[48:49], off offset:16
	v_lshlrev_b32_e32 v49, 16, v79
	v_lshlrev_b32_e32 v48, 16, v78
	v_add_f32_e32 v57, 1.0, v57
	v_mov_b32_e32 v52, v56
	v_pk_mul_f32 v[54:55], v[58:59], v[64:65] op_sel_hi:[1,0]
	v_mul_f32_e32 v56, 0xbfb8aa3b, v48
	v_rcp_f32_e32 v58, v57
	v_mul_f32_e32 v57, 0xbfb8aa3b, v49
	v_exp_f32_e32 v56, v56
	v_exp_f32_e32 v57, v57
	v_pk_mul_f32 v[52:53], v[52:53], v[64:65] op_sel_hi:[1,0]
	v_and_b32_e32 v51, 0xffff0000, v79
	v_add_f32_e32 v56, 1.0, v56
	v_add_f32_e32 v57, 1.0, v57
	v_rcp_f32_e32 v56, v56
	v_rcp_f32_e32 v57, v57
	s_nop 0
	v_pk_mul_f32 v[48:49], v[56:57], v[48:49]
	s_nop 0
	v_pk_mul_f32 v[48:49], v[52:53], v[48:49]
	s_nop 0
	v_and_b32_sdwa v53, v48, v229 dst_sel:DWORD dst_unused:UNUSED_PAD src0_sel:WORD_1 src1_sel:DWORD
	v_add3_u32 v53, v48, v53, s33
	v_mul_f32_e32 v48, 0xbfb8aa3b, v51
	v_exp_f32_e32 v48, v48
	v_and_b32_sdwa v52, v49, v229 dst_sel:DWORD dst_unused:UNUSED_PAD src0_sel:WORD_1 src1_sel:DWORD
	v_add3_u32 v52, v49, v52, s33
	v_add_f32_e32 v48, 1.0, v48
	v_rcp_f32_e32 v59, v48
	s_nop 0
	v_pk_mul_f32 v[48:49], v[58:59], v[50:51]
	s_nop 0
	v_pk_mul_f32 v[48:49], v[54:55], v[48:49]
	s_nop 0
	v_and_b32_sdwa v50, v49, v229 dst_sel:DWORD dst_unused:UNUSED_PAD src0_sel:WORD_1 src1_sel:DWORD
	v_add3_u32 v49, v49, v50, s33
	s_waitcnt vmcnt(14)
	v_and_b32_e32 v50, 0xffff0000, v76
	v_mul_f32_e32 v57, 0xbfb8aa3b, v50
	v_and_b32_sdwa v51, v48, v229 dst_sel:DWORD dst_unused:UNUSED_PAD src0_sel:WORD_1 src1_sel:DWORD
	v_exp_f32_e32 v57, v57
	v_add3_u32 v48, v48, v51, s33
	v_and_b32_e32 v49, 0xffff0000, v49
	v_and_b32_e32 v48, 0xffff0000, v48
	v_or_b32_sdwa v49, v49, v52 dst_sel:DWORD dst_unused:UNUSED_PAD src0_sel:DWORD src1_sel:WORD_1
	v_or_b32_sdwa v48, v48, v53 dst_sel:DWORD dst_unused:UNUSED_PAD src0_sel:DWORD src1_sel:WORD_1
	global_store_dwordx2 v[66:67], v[48:49], off offset:32
	v_lshlrev_b32_e32 v49, 16, v77
	v_lshlrev_b32_e32 v48, 16, v76
	v_add_f32_e32 v57, 1.0, v57
	v_mul_f32_e32 v56, 0xbfb8aa3b, v48
	v_rcp_f32_e32 v58, v57
	v_mul_f32_e32 v57, 0xbfb8aa3b, v49
	v_exp_f32_e32 v56, v56
	v_exp_f32_e32 v57, v57
	v_mov_b32_e32 v52, v60
	v_mov_b32_e32 v53, v62
	v_add_f32_e32 v56, 1.0, v56
	v_add_f32_e32 v57, 1.0, v57
	v_rcp_f32_e32 v56, v56
	v_rcp_f32_e32 v57, v57
	v_pk_mul_f32 v[52:53], v[52:53], v[64:65] op_sel_hi:[1,0]
	v_and_b32_e32 v51, 0xffff0000, v77
	v_mov_b32_e32 v62, v61
	v_pk_mul_f32 v[48:49], v[56:57], v[48:49]
	v_pk_mul_f32 v[54:55], v[62:63], v[64:65] op_sel_hi:[1,0]
	v_pk_mul_f32 v[48:49], v[52:53], v[48:49]
	s_nop 0
	v_and_b32_sdwa v53, v48, v229 dst_sel:DWORD dst_unused:UNUSED_PAD src0_sel:WORD_1 src1_sel:DWORD
	v_add3_u32 v53, v48, v53, s33
	v_mul_f32_e32 v48, 0xbfb8aa3b, v51
	v_exp_f32_e32 v48, v48
	v_and_b32_sdwa v52, v49, v229 dst_sel:DWORD dst_unused:UNUSED_PAD src0_sel:WORD_1 src1_sel:DWORD
	v_add3_u32 v52, v49, v52, s33
	v_add_f32_e32 v48, 1.0, v48
	v_rcp_f32_e32 v59, v48
	s_nop 0
	v_pk_mul_f32 v[48:49], v[58:59], v[50:51]
	s_nop 0
	v_pk_mul_f32 v[48:49], v[54:55], v[48:49]
	s_nop 0
	v_and_b32_sdwa v51, v48, v229 dst_sel:DWORD dst_unused:UNUSED_PAD src0_sel:WORD_1 src1_sel:DWORD
	v_and_b32_sdwa v50, v49, v229 dst_sel:DWORD dst_unused:UNUSED_PAD src0_sel:WORD_1 src1_sel:DWORD
	v_add3_u32 v48, v48, v51, s33
	v_add3_u32 v49, v49, v50, s33
	v_and_b32_e32 v48, 0xffff0000, v48
	v_and_b32_e32 v49, 0xffff0000, v49
	v_or_b32_sdwa v48, v48, v53 dst_sel:DWORD dst_unused:UNUSED_PAD src0_sel:DWORD src1_sel:WORD_1
	s_waitcnt vmcnt(14)
	v_and_b32_e32 v50, 0xffff0000, v74
	v_mov_b32_e32 v53, v34
	v_mov_b32_e32 v34, v33
	v_or_b32_sdwa v49, v49, v52 dst_sel:DWORD dst_unused:UNUSED_PAD src0_sel:DWORD src1_sel:WORD_1
	v_mov_b32_e32 v52, v32
	v_pk_mul_f32 v[32:33], v[34:35], v[64:65] op_sel_hi:[1,0]
	v_mul_f32_e32 v35, 0xbfb8aa3b, v50
	v_exp_f32_e32 v35, v35
	global_store_dwordx2 v[66:67], v[48:49], off offset:48
	v_lshlrev_b32_e32 v49, 16, v75
	v_lshlrev_b32_e32 v48, 16, v74
	v_add_f32_e32 v35, 1.0, v35
	v_mul_f32_e32 v34, 0xbfb8aa3b, v48
	v_rcp_f32_e32 v54, v35
	v_mul_f32_e32 v35, 0xbfb8aa3b, v49
	v_exp_f32_e32 v34, v34
	v_exp_f32_e32 v35, v35
	v_pk_mul_f32 v[52:53], v[52:53], v[64:65] op_sel_hi:[1,0]
	v_and_b32_e32 v51, 0xffff0000, v75
	v_add_f32_e32 v34, 1.0, v34
	v_add_f32_e32 v35, 1.0, v35
	v_rcp_f32_e32 v34, v34
	v_rcp_f32_e32 v35, v35
	s_nop 0
	v_pk_mul_f32 v[34:35], v[34:35], v[48:49]
	s_nop 0
	v_pk_mul_f32 v[34:35], v[52:53], v[34:35]
	s_nop 0
	v_and_b32_sdwa v49, v34, v229 dst_sel:DWORD dst_unused:UNUSED_PAD src0_sel:WORD_1 src1_sel:DWORD
	v_add3_u32 v49, v34, v49, s33
	v_mul_f32_e32 v34, 0xbfb8aa3b, v51
	v_exp_f32_e32 v34, v34
	v_and_b32_sdwa v48, v35, v229 dst_sel:DWORD dst_unused:UNUSED_PAD src0_sel:WORD_1 src1_sel:DWORD
	v_add3_u32 v48, v35, v48, s33
	v_add_f32_e32 v34, 1.0, v34
	v_rcp_f32_e32 v55, v34
	s_nop 0
	v_pk_mul_f32 v[34:35], v[54:55], v[50:51]
	s_nop 0
	v_pk_mul_f32 v[32:33], v[32:33], v[34:35]
	v_mov_b32_e32 v55, v18
	v_and_b32_sdwa v35, v32, v229 dst_sel:DWORD dst_unused:UNUSED_PAD src0_sel:WORD_1 src1_sel:DWORD
	v_and_b32_sdwa v34, v33, v229 dst_sel:DWORD dst_unused:UNUSED_PAD src0_sel:WORD_1 src1_sel:DWORD
	v_add3_u32 v32, v32, v35, s33
	v_add3_u32 v33, v33, v34, s33
	v_and_b32_e32 v32, 0xffff0000, v32
	v_and_b32_e32 v33, 0xffff0000, v33
	v_or_b32_sdwa v32, v32, v49 dst_sel:DWORD dst_unused:UNUSED_PAD src0_sel:DWORD src1_sel:WORD_1
	s_waitcnt vmcnt(14)
; __device__ __forceinline__ bf16_t f2bf(float f) { unsigned u = __float_as_uint(f); u += 0x7FFFu + ((u >> 16) & 1u); return (bf16_t)(u >> 16); }
; __device__ __forceinline__ float bperm_f(int addr, float v) { return __uint_as_float((unsigned)__builtin_amdgcn_ds_bpermute(addr, (int)__float_as_uint(v))); }
; __device__ __forceinline__ float silu(float x) { return x * __builtin_amdgcn_rcpf(1.0f + __expf(-x)); }
; __device__ __forceinline__ void attn_store_out(const f32x16& o0, const f32x16& o1, float inv, const bf16_t* __restrict__ gbase, int qt, bf16_t* __restrict__ yout, int b, int h, int hh) {
;     uint2 gws[2][4];
; #pragma unroll
;     for (int dt = 0; dt < 2; ++dt)
; #pragma unroll
;         for (int g = 0; g < 4; ++g) gws[dt][g] = *(const uint2*)(gbase + qt * 64 + dt * 32 + 8 * g + 4 * hh);
; #pragma unroll
;     for (int dt = 0; dt < 2; ++dt)
; #pragma unroll
;         for (int g = 0; g < 4; ++g) { const int d0 = dt * 32 + 8 * g + 4 * hh;
;             const uint2 gw = gws[dt][g];
;             const float g0 = __uint_as_float(gw.x << 16), g1 = __uint_as_float(gw.x & 0xffff0000u), g2 = __uint_as_float(gw.y << 16), g3 = __uint_as_float(gw.y & 0xffff0000u);
;             const float v0 = (dt ? o1[4 * g] : o0[4 * g]) * inv, v1 = (dt ? o1[4 * g + 1] : o0[4 * g + 1]) * inv, v2 = (dt ? o1[4 * g + 2] : o0[4 * g + 2]) * inv, v3 = (dt ? o1[4 * g + 3] : o0[4 * g + 3]) * inv;
;             uint2 w; w.x = (unsigned)f2bf(v0 * silu(g0)) | ((unsigned)f2bf(v1 * silu(g1)) << 16); w.y = (unsigned)f2bf(v2 * silu(g2)) | ((unsigned)f2bf(v3 * silu(g3)) << 16);
;             *(uint2*)(yout + (size_t)(b * SEQ + qt) * 1024 + h * 64 + d0) = w; }
; }
; __device__ __forceinline__ void natten_wave_task2(const bf16_t* __restrict__ proj, int b, int h, NatPol pA, NatPol pB, bf16_t* __restrict__ yout, int lane, LAS unsigned char* wl) {
;     ...
;     lA += bperm_f(xaddr, lA); lB += bperm_f(xaddr, lB);
;     attn_store_out(oA0, oA1, 1.0f / lA, gbase, qtA, yout, b, h, hh);
;     attn_store_out(oB0, oB1, 1.0f / lB, gbase, qtB, yout, b, h, hh);
	v_and_b32_e32 v34, 0xffff0000, v72
	v_mov_b32_e32 v49, v38
	v_mov_b32_e32 v38, v37
	v_or_b32_sdwa v33, v33, v48 dst_sel:DWORD dst_unused:UNUSED_PAD src0_sel:DWORD src1_sel:WORD_1
	v_mov_b32_e32 v48, v36
	v_pk_mul_f32 v[36:37], v[38:39], v[64:65] op_sel_hi:[1,0]
	v_mul_f32_e32 v39, 0xbfb8aa3b, v34
	v_exp_f32_e32 v39, v39
	global_store_dwordx2 v[66:67], v[32:33], off offset:64
	v_lshlrev_b32_e32 v33, 16, v73
	v_lshlrev_b32_e32 v32, 16, v72
	v_add_f32_e32 v39, 1.0, v39
	v_mul_f32_e32 v38, 0xbfb8aa3b, v32
	v_rcp_f32_e32 v50, v39
	v_mul_f32_e32 v39, 0xbfb8aa3b, v33
	v_exp_f32_e32 v38, v38
	v_exp_f32_e32 v39, v39
	v_pk_mul_f32 v[48:49], v[48:49], v[64:65] op_sel_hi:[1,0]
	v_and_b32_e32 v35, 0xffff0000, v73
	v_add_f32_e32 v38, 1.0, v38
	v_add_f32_e32 v39, 1.0, v39
	v_rcp_f32_e32 v38, v38
	v_rcp_f32_e32 v39, v39
	v_mov_b32_e32 v18, v17
	v_mov_b32_e32 v54, v16
	v_pk_mul_f32 v[32:33], v[38:39], v[32:33]
	s_nop 0
	v_pk_mul_f32 v[32:33], v[48:49], v[32:33]
	s_nop 0
	v_and_b32_sdwa v39, v32, v229 dst_sel:DWORD dst_unused:UNUSED_PAD src0_sel:WORD_1 src1_sel:DWORD
	v_add3_u32 v39, v32, v39, s33
	v_mul_f32_e32 v32, 0xbfb8aa3b, v35
	v_exp_f32_e32 v32, v32
	v_and_b32_sdwa v38, v33, v229 dst_sel:DWORD dst_unused:UNUSED_PAD src0_sel:WORD_1 src1_sel:DWORD
	v_add3_u32 v38, v33, v38, s33
	v_add_f32_e32 v32, 1.0, v32
	v_rcp_f32_e32 v51, v32
	s_nop 0
	v_pk_mul_f32 v[32:33], v[50:51], v[34:35]
	s_nop 0
	v_pk_mul_f32 v[32:33], v[36:37], v[32:33]
	v_mov_b32_e32 v37, v42
	v_and_b32_sdwa v34, v33, v229 dst_sel:DWORD dst_unused:UNUSED_PAD src0_sel:WORD_1 src1_sel:DWORD
	v_add3_u32 v33, v33, v34, s33
	s_waitcnt vmcnt(14)
	v_and_b32_e32 v34, 0xffff0000, v70
	v_mov_b32_e32 v42, v41
	v_mul_f32_e32 v41, 0xbfb8aa3b, v34
	v_and_b32_sdwa v35, v32, v229 dst_sel:DWORD dst_unused:UNUSED_PAD src0_sel:WORD_1 src1_sel:DWORD
	v_exp_f32_e32 v41, v41
	v_add3_u32 v32, v32, v35, s33
	v_and_b32_e32 v33, 0xffff0000, v33
	v_and_b32_e32 v32, 0xffff0000, v32
	v_or_b32_sdwa v33, v33, v38 dst_sel:DWORD dst_unused:UNUSED_PAD src0_sel:DWORD src1_sel:WORD_1
	v_or_b32_sdwa v32, v32, v39 dst_sel:DWORD dst_unused:UNUSED_PAD src0_sel:DWORD src1_sel:WORD_1
	global_store_dwordx2 v[66:67], v[32:33], off offset:80
	v_lshlrev_b32_e32 v33, 16, v71
	v_lshlrev_b32_e32 v32, 16, v70
	v_add_f32_e32 v41, 1.0, v41
	v_mov_b32_e32 v36, v40
	v_pk_mul_f32 v[38:39], v[42:43], v[64:65] op_sel_hi:[1,0]
	v_mul_f32_e32 v40, 0xbfb8aa3b, v32
	v_rcp_f32_e32 v42, v41
	v_mul_f32_e32 v41, 0xbfb8aa3b, v33
	v_exp_f32_e32 v40, v40
	v_exp_f32_e32 v41, v41
	v_pk_mul_f32 v[36:37], v[36:37], v[64:65] op_sel_hi:[1,0]
	v_and_b32_e32 v35, 0xffff0000, v71
	v_add_f32_e32 v40, 1.0, v40
	v_add_f32_e32 v41, 1.0, v41
	v_rcp_f32_e32 v40, v40
	v_rcp_f32_e32 v41, v41
	s_nop 0
	v_pk_mul_f32 v[32:33], v[40:41], v[32:33]
	s_nop 0
	v_pk_mul_f32 v[32:33], v[36:37], v[32:33]
	s_nop 0
	v_and_b32_sdwa v37, v32, v229 dst_sel:DWORD dst_unused:UNUSED_PAD src0_sel:WORD_1 src1_sel:DWORD
	v_add3_u32 v37, v32, v37, s33
	v_mul_f32_e32 v32, 0xbfb8aa3b, v35
	v_exp_f32_e32 v32, v32
	v_and_b32_sdwa v36, v33, v229 dst_sel:DWORD dst_unused:UNUSED_PAD src0_sel:WORD_1 src1_sel:DWORD
	v_add3_u32 v36, v33, v36, s33
	v_add_f32_e32 v32, 1.0, v32
	v_rcp_f32_e32 v43, v32
	s_nop 0
	v_pk_mul_f32 v[32:33], v[42:43], v[34:35]
	s_nop 0
	v_pk_mul_f32 v[32:33], v[38:39], v[32:33]
	s_nop 0
	v_and_b32_sdwa v34, v33, v229 dst_sel:DWORD dst_unused:UNUSED_PAD src0_sel:WORD_1 src1_sel:DWORD
	v_add3_u32 v33, v33, v34, s33
	s_waitcnt vmcnt(14)
	v_and_b32_e32 v34, 0xffff0000, v68
	v_mul_f32_e32 v41, 0xbfb8aa3b, v34
	v_exp_f32_e32 v41, v41
	v_and_b32_sdwa v35, v32, v229 dst_sel:DWORD dst_unused:UNUSED_PAD src0_sel:WORD_1 src1_sel:DWORD
	v_add3_u32 v32, v32, v35, s33
	v_and_b32_e32 v33, 0xffff0000, v33
	v_and_b32_e32 v32, 0xffff0000, v32
	v_or_b32_sdwa v33, v33, v36 dst_sel:DWORD dst_unused:UNUSED_PAD src0_sel:DWORD src1_sel:WORD_1
	v_or_b32_sdwa v32, v32, v37 dst_sel:DWORD dst_unused:UNUSED_PAD src0_sel:DWORD src1_sel:WORD_1
	v_lshlrev_b32_e32 v37, 16, v69
	v_lshlrev_b32_e32 v36, 16, v68
	v_add_f32_e32 v41, 1.0, v41
	v_mul_f32_e32 v40, 0xbfb8aa3b, v36
	v_rcp_f32_e32 v42, v41
	v_mul_f32_e32 v41, 0xbfb8aa3b, v37
	v_exp_f32_e32 v40, v40
	v_exp_f32_e32 v41, v41
	global_store_dwordx2 v[66:67], v[32:33], off offset:96
	v_mov_b32_e32 v32, v44
	v_add_f32_e32 v40, 1.0, v40
	v_add_f32_e32 v41, 1.0, v41
	v_rcp_f32_e32 v40, v40
	v_rcp_f32_e32 v41, v41
	v_mov_b32_e32 v33, v46
	v_pk_mul_f32 v[32:33], v[32:33], v[64:65] op_sel_hi:[1,0]
	v_and_b32_e32 v35, 0xffff0000, v69
	v_pk_mul_f32 v[36:37], v[40:41], v[36:37]
	v_mov_b32_e32 v46, v45
	v_pk_mul_f32 v[32:33], v[32:33], v[36:37]
	v_pk_mul_f32 v[38:39], v[46:47], v[64:65] op_sel_hi:[1,0]
	v_and_b32_sdwa v37, v32, v229 dst_sel:DWORD dst_unused:UNUSED_PAD src0_sel:WORD_1 src1_sel:DWORD
	v_add3_u32 v37, v32, v37, s33
	v_mul_f32_e32 v32, 0xbfb8aa3b, v35
	v_exp_f32_e32 v32, v32
	v_and_b32_sdwa v36, v33, v229 dst_sel:DWORD dst_unused:UNUSED_PAD src0_sel:WORD_1 src1_sel:DWORD
	v_add3_u32 v36, v33, v36, s33
	v_add_f32_e32 v32, 1.0, v32
	v_rcp_f32_e32 v43, v32
	s_nop 0
	v_pk_mul_f32 v[32:33], v[42:43], v[34:35]
	s_nop 0
	v_pk_mul_f32 v[32:33], v[38:39], v[32:33]
	s_nop 0
	v_and_b32_sdwa v34, v33, v229 dst_sel:DWORD dst_unused:UNUSED_PAD src0_sel:WORD_1 src1_sel:DWORD
	v_and_b32_sdwa v35, v32, v229 dst_sel:DWORD dst_unused:UNUSED_PAD src0_sel:WORD_1 src1_sel:DWORD
	v_add3_u32 v33, v33, v34, s33
	v_add3_u32 v32, v32, v35, s33
	v_and_b32_e32 v33, 0xffff0000, v33
	v_and_b32_e32 v32, 0xffff0000, v32
	v_or_b32_sdwa v33, v33, v36 dst_sel:DWORD dst_unused:UNUSED_PAD src0_sel:DWORD src1_sel:WORD_1
	v_or_b32_sdwa v32, v32, v37 dst_sel:DWORD dst_unused:UNUSED_PAD src0_sel:DWORD src1_sel:WORD_1
	global_store_dwordx2 v[66:67], v[32:33], off offset:112
	v_div_scale_f32 v32, s[0:1], v65, v65, 1.0
	v_rcp_f32_e32 v33, v32
	v_readlane_b32 s0, v252, 53
	s_add_i32 s52, s52, s0
	s_cmpk_gt_i32 s52, 0x1fff
	v_fma_f32 v34, -v32, v33, 1.0
	v_fmac_f32_e32 v33, v34, v33
	v_div_scale_f32 v34, vcc, 1.0, v65, 1.0
	v_mul_f32_e32 v35, v34, v33
	v_fma_f32 v36, -v32, v35, v34
	v_fmac_f32_e32 v35, v36, v33
	v_fma_f32 v32, -v32, v35, v34
	v_div_fmas_f32 v32, v32, v33, v35
	v_lshl_add_u64 v[34:35], v[166:167], 1, s[6:7]
	v_lshl_add_u64 v[34:35], v[34:35], 0, v[164:165]
	s_waitcnt vmcnt(8)
; __device__ __forceinline__ bf16_t f2bf(float f) { unsigned u = __float_as_uint(f); u += 0x7FFFu + ((u >> 16) & 1u); return (bf16_t)(u >> 16); }
; __device__ __forceinline__ float silu(float x) { return x * __builtin_amdgcn_rcpf(1.0f + __expf(-x)); }
; __device__ __forceinline__ void attn_store_out(const f32x16& o0, const f32x16& o1, float inv, const bf16_t* __restrict__ gbase, int qt, bf16_t* __restrict__ yout, int b, int h, int hh) {
;     uint2 gws[2][4];
; #pragma unroll
;     for (int dt = 0; dt < 2; ++dt)
; #pragma unroll
;         for (int g = 0; g < 4; ++g) gws[dt][g] = *(const uint2*)(gbase + qt * 64 + dt * 32 + 8 * g + 4 * hh);
; #pragma unroll
;     for (int dt = 0; dt < 2; ++dt)
; #pragma unroll
;         for (int g = 0; g < 4; ++g) { const int d0 = dt * 32 + 8 * g + 4 * hh;
;             const uint2 gw = gws[dt][g];
;             const float g0 = __uint_as_float(gw.x << 16), g1 = __uint_as_float(gw.x & 0xffff0000u), g2 = __uint_as_float(gw.y << 16), g3 = __uint_as_float(gw.y & 0xffff0000u);
;             const float v0 = (dt ? o1[4 * g] : o0[4 * g]) * inv, v1 = (dt ? o1[4 * g + 1] : o0[4 * g + 1]) * inv, v2 = (dt ? o1[4 * g + 2] : o0[4 * g + 2]) * inv, v3 = (dt ? o1[4 * g + 3] : o0[4 * g + 3]) * inv;
;             uint2 w; w.x = (unsigned)f2bf(v0 * silu(g0)) | ((unsigned)f2bf(v1 * silu(g1)) << 16); w.y = (unsigned)f2bf(v2 * silu(g2)) | ((unsigned)f2bf(v3 * silu(g3)) << 16);
;             *(uint2*)(yout + (size_t)(b * SEQ + qt) * 1024 + h * 64 + d0) = w; }
; }
	v_mov_b32_e32 v48, v92
	v_mov_b32_e32 v49, v93
	v_mov_b32_e32 v50, v94
	v_mov_b32_e32 v51, v95
	v_mov_b32_e32 v46, v96
	v_mov_b32_e32 v47, v97
	v_mov_b32_e32 v44, v98
	v_mov_b32_e32 v45, v99
	v_mov_b32_e32 v42, v100
	v_mov_b32_e32 v43, v101
	v_mov_b32_e32 v40, v102
	v_mov_b32_e32 v41, v103
	v_mov_b32_e32 v38, v104
	v_mov_b32_e32 v39, v105
	v_mov_b32_e32 v36, v106
	v_mov_b32_e32 v37, v107
	v_div_fixup_f32 v32, v32, v65, 1.0
	v_pk_mul_f32 v[16:17], v[18:19], v[32:33] op_sel_hi:[1,0]
	v_pk_mul_f32 v[54:55], v[54:55], v[32:33] op_sel_hi:[1,0]
	v_add_u32_e32 v34, s10, v204
	v_ashrrev_i32_e32 v35, 31, v34
	v_lshlrev_b64 v[34:35], 11, v[34:35]
	v_lshl_add_u64 v[34:35], s[14:15], 0, v[34:35]
	v_lshl_add_u64 v[34:35], v[34:35], 0, s[62:63]
	v_lshl_add_u64 v[34:35], v[34:35], 0, v[164:165]
	v_lshlrev_b32_e32 v52, 16, v48
	v_and_b32_e32 v48, 0xffff0000, v48
	v_mul_f32_e32 v19, 0xbfb8aa3b, v48
	v_exp_f32_e32 v19, v19
	v_lshlrev_b32_e32 v53, 16, v49
	v_mul_f32_e32 v18, 0xbfb8aa3b, v52
	v_exp_f32_e32 v18, v18
	v_add_f32_e32 v19, 1.0, v19
	v_rcp_f32_e32 v56, v19
	v_mul_f32_e32 v19, 0xbfb8aa3b, v53
	v_exp_f32_e32 v19, v19
	v_add_f32_e32 v18, 1.0, v18
	v_rcp_f32_e32 v18, v18
	v_and_b32_e32 v49, 0xffff0000, v49
	v_add_f32_e32 v19, 1.0, v19
	v_rcp_f32_e32 v19, v19
	s_nop 0
	v_pk_mul_f32 v[18:19], v[18:19], v[52:53]
	s_nop 0
	v_pk_mul_f32 v[18:19], v[54:55], v[18:19]
	s_nop 0
	v_and_b32_sdwa v52, v18, v229 dst_sel:DWORD dst_unused:UNUSED_PAD src0_sel:WORD_1 src1_sel:DWORD
	v_add3_u32 v52, v18, v52, s33
	v_mul_f32_e32 v18, 0xbfb8aa3b, v49
	v_exp_f32_e32 v18, v18
	v_and_b32_sdwa v33, v19, v229 dst_sel:DWORD dst_unused:UNUSED_PAD src0_sel:WORD_1 src1_sel:DWORD
	v_add3_u32 v33, v19, v33, s33
	v_add_f32_e32 v18, 1.0, v18
	v_rcp_f32_e32 v57, v18
	s_nop 0
	v_pk_mul_f32 v[18:19], v[56:57], v[48:49]
	s_nop 0
	v_pk_mul_f32 v[16:17], v[16:17], v[18:19]
	v_mov_b32_e32 v49, v22
	v_and_b32_sdwa v18, v17, v229 dst_sel:DWORD dst_unused:UNUSED_PAD src0_sel:WORD_1 src1_sel:DWORD
	v_add3_u32 v17, v17, v18, s33
	v_and_b32_e32 v18, 0xffff0000, v50
	v_mov_b32_e32 v22, v21
	v_mov_b32_e32 v48, v20
	v_pk_mul_f32 v[20:21], v[22:23], v[32:33] op_sel_hi:[1,0]
	v_mul_f32_e32 v23, 0xbfb8aa3b, v18
	v_and_b32_sdwa v19, v16, v229 dst_sel:DWORD dst_unused:UNUSED_PAD src0_sel:WORD_1 src1_sel:DWORD
	v_exp_f32_e32 v23, v23
	v_add3_u32 v16, v16, v19, s33
	v_and_b32_e32 v17, 0xffff0000, v17
	v_and_b32_e32 v16, 0xffff0000, v16
	v_or_b32_sdwa v17, v17, v33 dst_sel:DWORD dst_unused:UNUSED_PAD src0_sel:DWORD src1_sel:WORD_1
	v_or_b32_sdwa v16, v16, v52 dst_sel:DWORD dst_unused:UNUSED_PAD src0_sel:DWORD src1_sel:WORD_1
	global_store_dwordx2 v[34:35], v[16:17], off
	v_lshlrev_b32_e32 v17, 16, v51
	v_lshlrev_b32_e32 v16, 16, v50
	v_add_f32_e32 v23, 1.0, v23
	v_mul_f32_e32 v22, 0xbfb8aa3b, v16
	v_rcp_f32_e32 v50, v23
	v_mul_f32_e32 v23, 0xbfb8aa3b, v17
	v_exp_f32_e32 v22, v22
	v_exp_f32_e32 v23, v23
	v_pk_mul_f32 v[48:49], v[48:49], v[32:33] op_sel_hi:[1,0]
	v_and_b32_e32 v19, 0xffff0000, v51
	v_add_f32_e32 v22, 1.0, v22
	v_add_f32_e32 v23, 1.0, v23
	v_rcp_f32_e32 v22, v22
	v_rcp_f32_e32 v23, v23
	s_nop 0
	v_pk_mul_f32 v[16:17], v[22:23], v[16:17]
	s_nop 0
	v_pk_mul_f32 v[16:17], v[48:49], v[16:17]
	s_nop 0
	v_and_b32_sdwa v23, v16, v229 dst_sel:DWORD dst_unused:UNUSED_PAD src0_sel:WORD_1 src1_sel:DWORD
	v_add3_u32 v23, v16, v23, s33
	v_mul_f32_e32 v16, 0xbfb8aa3b, v19
	v_exp_f32_e32 v16, v16
	v_and_b32_sdwa v22, v17, v229 dst_sel:DWORD dst_unused:UNUSED_PAD src0_sel:WORD_1 src1_sel:DWORD
	v_add3_u32 v22, v17, v22, s33
	v_add_f32_e32 v16, 1.0, v16
	v_rcp_f32_e32 v51, v16
	s_nop 0
	v_pk_mul_f32 v[16:17], v[50:51], v[18:19]
	s_nop 0
	v_pk_mul_f32 v[16:17], v[20:21], v[16:17]
	v_mov_b32_e32 v21, v26
	v_and_b32_sdwa v18, v17, v229 dst_sel:DWORD dst_unused:UNUSED_PAD src0_sel:WORD_1 src1_sel:DWORD
	v_add3_u32 v17, v17, v18, s33
	v_and_b32_e32 v18, 0xffff0000, v46
	v_mov_b32_e32 v26, v25
	v_mul_f32_e32 v25, 0xbfb8aa3b, v18
	v_and_b32_sdwa v19, v16, v229 dst_sel:DWORD dst_unused:UNUSED_PAD src0_sel:WORD_1 src1_sel:DWORD
	v_exp_f32_e32 v25, v25
	v_add3_u32 v16, v16, v19, s33
	v_and_b32_e32 v17, 0xffff0000, v17
	v_and_b32_e32 v16, 0xffff0000, v16
	v_or_b32_sdwa v17, v17, v22 dst_sel:DWORD dst_unused:UNUSED_PAD src0_sel:DWORD src1_sel:WORD_1
	v_or_b32_sdwa v16, v16, v23 dst_sel:DWORD dst_unused:UNUSED_PAD src0_sel:DWORD src1_sel:WORD_1
	global_store_dwordx2 v[34:35], v[16:17], off offset:16
	v_lshlrev_b32_e32 v17, 16, v47
	v_lshlrev_b32_e32 v16, 16, v46
	v_add_f32_e32 v25, 1.0, v25
	v_mov_b32_e32 v20, v24
	v_pk_mul_f32 v[22:23], v[26:27], v[32:33] op_sel_hi:[1,0]
	v_mul_f32_e32 v24, 0xbfb8aa3b, v16
	v_rcp_f32_e32 v26, v25
	v_mul_f32_e32 v25, 0xbfb8aa3b, v17
	v_exp_f32_e32 v24, v24
	v_exp_f32_e32 v25, v25
	v_pk_mul_f32 v[20:21], v[20:21], v[32:33] op_sel_hi:[1,0]
	v_and_b32_e32 v19, 0xffff0000, v47
	v_add_f32_e32 v24, 1.0, v24
	v_add_f32_e32 v25, 1.0, v25
	v_rcp_f32_e32 v24, v24
	v_rcp_f32_e32 v25, v25
	s_nop 0
	v_pk_mul_f32 v[16:17], v[24:25], v[16:17]
	s_nop 0
	v_pk_mul_f32 v[16:17], v[20:21], v[16:17]
	s_nop 0
	v_and_b32_sdwa v21, v16, v229 dst_sel:DWORD dst_unused:UNUSED_PAD src0_sel:WORD_1 src1_sel:DWORD
	v_add3_u32 v21, v16, v21, s33
	v_mul_f32_e32 v16, 0xbfb8aa3b, v19
	v_exp_f32_e32 v16, v16
	v_and_b32_sdwa v20, v17, v229 dst_sel:DWORD dst_unused:UNUSED_PAD src0_sel:WORD_1 src1_sel:DWORD
	v_add3_u32 v20, v17, v20, s33
	v_add_f32_e32 v16, 1.0, v16
	v_rcp_f32_e32 v27, v16
	s_nop 0
	v_pk_mul_f32 v[16:17], v[26:27], v[18:19]
	s_nop 0
	v_pk_mul_f32 v[16:17], v[22:23], v[16:17]
	s_nop 0
	v_and_b32_sdwa v18, v17, v229 dst_sel:DWORD dst_unused:UNUSED_PAD src0_sel:WORD_1 src1_sel:DWORD
	v_add3_u32 v17, v17, v18, s33
; __device__ __forceinline__ bf16_t f2bf(float f) { unsigned u = __float_as_uint(f); u += 0x7FFFu + ((u >> 16) & 1u); return (bf16_t)(u >> 16); }
; __device__ __forceinline__ float silu(float x) { return x * __builtin_amdgcn_rcpf(1.0f + __expf(-x)); }
; __device__ __forceinline__ void attn_store_out(const f32x16& o0, const f32x16& o1, float inv, const bf16_t* __restrict__ gbase, int qt, bf16_t* __restrict__ yout, int b, int h, int hh) {
;     uint2 gws[2][4];
; #pragma unroll
;     for (int dt = 0; dt < 2; ++dt)
; #pragma unroll
;         for (int g = 0; g < 4; ++g) gws[dt][g] = *(const uint2*)(gbase + qt * 64 + dt * 32 + 8 * g + 4 * hh);
; #pragma unroll
;     for (int dt = 0; dt < 2; ++dt)
; #pragma unroll
;         for (int g = 0; g < 4; ++g) { const int d0 = dt * 32 + 8 * g + 4 * hh;
;             const uint2 gw = gws[dt][g];
;             const float g0 = __uint_as_float(gw.x << 16), g1 = __uint_as_float(gw.x & 0xffff0000u), g2 = __uint_as_float(gw.y << 16), g3 = __uint_as_float(gw.y & 0xffff0000u);
;             const float v0 = (dt ? o1[4 * g] : o0[4 * g]) * inv, v1 = (dt ? o1[4 * g + 1] : o0[4 * g + 1]) * inv, v2 = (dt ? o1[4 * g + 2] : o0[4 * g + 2]) * inv, v3 = (dt ? o1[4 * g + 3] : o0[4 * g + 3]) * inv;
;             uint2 w; w.x = (unsigned)f2bf(v0 * silu(g0)) | ((unsigned)f2bf(v1 * silu(g1)) << 16); w.y = (unsigned)f2bf(v2 * silu(g2)) | ((unsigned)f2bf(v3 * silu(g3)) << 16);
;             *(uint2*)(yout + (size_t)(b * SEQ + qt) * 1024 + h * 64 + d0) = w; }
; }
	v_and_b32_e32 v18, 0xffff0000, v44
	v_mul_f32_e32 v25, 0xbfb8aa3b, v18
	v_and_b32_sdwa v19, v16, v229 dst_sel:DWORD dst_unused:UNUSED_PAD src0_sel:WORD_1 src1_sel:DWORD
	v_exp_f32_e32 v25, v25
	v_add3_u32 v16, v16, v19, s33
	v_and_b32_e32 v17, 0xffff0000, v17
	v_and_b32_e32 v16, 0xffff0000, v16
	v_or_b32_sdwa v17, v17, v20 dst_sel:DWORD dst_unused:UNUSED_PAD src0_sel:DWORD src1_sel:WORD_1
	v_or_b32_sdwa v16, v16, v21 dst_sel:DWORD dst_unused:UNUSED_PAD src0_sel:DWORD src1_sel:WORD_1
	global_store_dwordx2 v[34:35], v[16:17], off offset:32
	v_lshlrev_b32_e32 v17, 16, v45
	v_lshlrev_b32_e32 v16, 16, v44
	v_add_f32_e32 v25, 1.0, v25
	v_mul_f32_e32 v24, 0xbfb8aa3b, v16
	v_rcp_f32_e32 v26, v25
	v_mul_f32_e32 v25, 0xbfb8aa3b, v17
	v_exp_f32_e32 v24, v24
	v_exp_f32_e32 v25, v25
	v_mov_b32_e32 v20, v28
	v_mov_b32_e32 v21, v30
	v_add_f32_e32 v24, 1.0, v24
	v_add_f32_e32 v25, 1.0, v25
	v_rcp_f32_e32 v24, v24
	v_rcp_f32_e32 v25, v25
	v_pk_mul_f32 v[20:21], v[20:21], v[32:33] op_sel_hi:[1,0]
	v_and_b32_e32 v19, 0xffff0000, v45
	v_mov_b32_e32 v30, v29
	v_pk_mul_f32 v[16:17], v[24:25], v[16:17]
	v_pk_mul_f32 v[22:23], v[30:31], v[32:33] op_sel_hi:[1,0]
	v_pk_mul_f32 v[16:17], v[20:21], v[16:17]
	s_nop 0
	v_and_b32_sdwa v21, v16, v229 dst_sel:DWORD dst_unused:UNUSED_PAD src0_sel:WORD_1 src1_sel:DWORD
	v_add3_u32 v21, v16, v21, s33
	v_mul_f32_e32 v16, 0xbfb8aa3b, v19
	v_exp_f32_e32 v16, v16
	v_and_b32_sdwa v20, v17, v229 dst_sel:DWORD dst_unused:UNUSED_PAD src0_sel:WORD_1 src1_sel:DWORD
	v_add3_u32 v20, v17, v20, s33
	v_add_f32_e32 v16, 1.0, v16
	v_rcp_f32_e32 v27, v16
	s_nop 0
	v_pk_mul_f32 v[16:17], v[26:27], v[18:19]
	s_nop 0
	v_pk_mul_f32 v[16:17], v[22:23], v[16:17]
	s_nop 0
	v_and_b32_sdwa v19, v16, v229 dst_sel:DWORD dst_unused:UNUSED_PAD src0_sel:WORD_1 src1_sel:DWORD
	v_and_b32_sdwa v18, v17, v229 dst_sel:DWORD dst_unused:UNUSED_PAD src0_sel:WORD_1 src1_sel:DWORD
	v_add3_u32 v16, v16, v19, s33
	v_add3_u32 v17, v17, v18, s33
	v_and_b32_e32 v16, 0xffff0000, v16
	v_and_b32_e32 v17, 0xffff0000, v17
	v_or_b32_sdwa v16, v16, v21 dst_sel:DWORD dst_unused:UNUSED_PAD src0_sel:DWORD src1_sel:WORD_1
	v_and_b32_e32 v18, 0xffff0000, v42
	v_mov_b32_e32 v21, v2
	v_mov_b32_e32 v2, v1
	v_or_b32_sdwa v17, v17, v20 dst_sel:DWORD dst_unused:UNUSED_PAD src0_sel:DWORD src1_sel:WORD_1
	v_mov_b32_e32 v20, v0
	v_pk_mul_f32 v[0:1], v[2:3], v[32:33] op_sel_hi:[1,0]
	v_mul_f32_e32 v3, 0xbfb8aa3b, v18
	v_exp_f32_e32 v3, v3
	global_store_dwordx2 v[34:35], v[16:17], off offset:48
	v_lshlrev_b32_e32 v17, 16, v43
	v_lshlrev_b32_e32 v16, 16, v42
	v_add_f32_e32 v3, 1.0, v3
	v_mul_f32_e32 v2, 0xbfb8aa3b, v16
	v_rcp_f32_e32 v22, v3
	v_mul_f32_e32 v3, 0xbfb8aa3b, v17
	v_exp_f32_e32 v2, v2
	v_exp_f32_e32 v3, v3
	v_pk_mul_f32 v[20:21], v[20:21], v[32:33] op_sel_hi:[1,0]
	v_and_b32_e32 v19, 0xffff0000, v43
	v_add_f32_e32 v2, 1.0, v2
	v_add_f32_e32 v3, 1.0, v3
	v_rcp_f32_e32 v2, v2
	v_rcp_f32_e32 v3, v3
	s_nop 0
	v_pk_mul_f32 v[2:3], v[2:3], v[16:17]
	s_nop 0
	v_pk_mul_f32 v[2:3], v[20:21], v[2:3]
	s_nop 0
	v_and_b32_sdwa v17, v2, v229 dst_sel:DWORD dst_unused:UNUSED_PAD src0_sel:WORD_1 src1_sel:DWORD
	v_add3_u32 v17, v2, v17, s33
	v_mul_f32_e32 v2, 0xbfb8aa3b, v19
	v_exp_f32_e32 v2, v2
	v_and_b32_sdwa v16, v3, v229 dst_sel:DWORD dst_unused:UNUSED_PAD src0_sel:WORD_1 src1_sel:DWORD
	v_add3_u32 v16, v3, v16, s33
	v_add_f32_e32 v2, 1.0, v2
	v_rcp_f32_e32 v23, v2
	s_nop 0
	v_pk_mul_f32 v[2:3], v[22:23], v[18:19]
	s_nop 0
	v_pk_mul_f32 v[0:1], v[0:1], v[2:3]
	s_nop 0
	v_and_b32_sdwa v3, v0, v229 dst_sel:DWORD dst_unused:UNUSED_PAD src0_sel:WORD_1 src1_sel:DWORD
	v_and_b32_sdwa v2, v1, v229 dst_sel:DWORD dst_unused:UNUSED_PAD src0_sel:WORD_1 src1_sel:DWORD
	v_add3_u32 v0, v0, v3, s33
	v_add3_u32 v1, v1, v2, s33
	v_and_b32_e32 v0, 0xffff0000, v0
	v_and_b32_e32 v1, 0xffff0000, v1
	v_or_b32_sdwa v0, v0, v17 dst_sel:DWORD dst_unused:UNUSED_PAD src0_sel:DWORD src1_sel:WORD_1
	v_and_b32_e32 v2, 0xffff0000, v40
	v_mov_b32_e32 v17, v6
	v_mov_b32_e32 v6, v5
	v_or_b32_sdwa v1, v1, v16 dst_sel:DWORD dst_unused:UNUSED_PAD src0_sel:DWORD src1_sel:WORD_1
	v_mov_b32_e32 v16, v4
	v_pk_mul_f32 v[4:5], v[6:7], v[32:33] op_sel_hi:[1,0]
	v_mul_f32_e32 v7, 0xbfb8aa3b, v2
	v_exp_f32_e32 v7, v7
	global_store_dwordx2 v[34:35], v[0:1], off offset:64
	v_lshlrev_b32_e32 v1, 16, v41
	v_lshlrev_b32_e32 v0, 16, v40
	v_add_f32_e32 v7, 1.0, v7
	v_mul_f32_e32 v6, 0xbfb8aa3b, v0
	v_rcp_f32_e32 v18, v7
	v_mul_f32_e32 v7, 0xbfb8aa3b, v1
	v_exp_f32_e32 v6, v6
	v_exp_f32_e32 v7, v7
	v_pk_mul_f32 v[16:17], v[16:17], v[32:33] op_sel_hi:[1,0]
	v_and_b32_e32 v3, 0xffff0000, v41
	v_add_f32_e32 v6, 1.0, v6
	v_add_f32_e32 v7, 1.0, v7
; __device__ __forceinline__ bf16_t f2bf(float f) { unsigned u = __float_as_uint(f); u += 0x7FFFu + ((u >> 16) & 1u); return (bf16_t)(u >> 16); }
; __device__ __forceinline__ float silu(float x) { return x * __builtin_amdgcn_rcpf(1.0f + __expf(-x)); }
; __device__ __forceinline__ void attn_store_out(const f32x16& o0, const f32x16& o1, float inv, const bf16_t* __restrict__ gbase, int qt, bf16_t* __restrict__ yout, int b, int h, int hh) {
;     uint2 gws[2][4];
; #pragma unroll
;     for (int dt = 0; dt < 2; ++dt)
; #pragma unroll
;         for (int g = 0; g < 4; ++g) gws[dt][g] = *(const uint2*)(gbase + qt * 64 + dt * 32 + 8 * g + 4 * hh);
; #pragma unroll
;     for (int dt = 0; dt < 2; ++dt)
; #pragma unroll
;         for (int g = 0; g < 4; ++g) { const int d0 = dt * 32 + 8 * g + 4 * hh;
;             const uint2 gw = gws[dt][g];
;             const float g0 = __uint_as_float(gw.x << 16), g1 = __uint_as_float(gw.x & 0xffff0000u), g2 = __uint_as_float(gw.y << 16), g3 = __uint_as_float(gw.y & 0xffff0000u);
;             const float v0 = (dt ? o1[4 * g] : o0[4 * g]) * inv, v1 = (dt ? o1[4 * g + 1] : o0[4 * g + 1]) * inv, v2 = (dt ? o1[4 * g + 2] : o0[4 * g + 2]) * inv, v3 = (dt ? o1[4 * g + 3] : o0[4 * g + 3]) * inv;
;             uint2 w; w.x = (unsigned)f2bf(v0 * silu(g0)) | ((unsigned)f2bf(v1 * silu(g1)) << 16); w.y = (unsigned)f2bf(v2 * silu(g2)) | ((unsigned)f2bf(v3 * silu(g3)) << 16);
;             *(uint2*)(yout + (size_t)(b * SEQ + qt) * 1024 + h * 64 + d0) = w; }
; }
	v_rcp_f32_e32 v6, v6
	v_rcp_f32_e32 v7, v7
	s_nop 0
	v_pk_mul_f32 v[0:1], v[6:7], v[0:1]
	s_nop 0
	v_pk_mul_f32 v[0:1], v[16:17], v[0:1]
	s_nop 0
	v_and_b32_sdwa v7, v0, v229 dst_sel:DWORD dst_unused:UNUSED_PAD src0_sel:WORD_1 src1_sel:DWORD
	v_add3_u32 v7, v0, v7, s33
	v_mul_f32_e32 v0, 0xbfb8aa3b, v3
	v_exp_f32_e32 v0, v0
	v_and_b32_sdwa v6, v1, v229 dst_sel:DWORD dst_unused:UNUSED_PAD src0_sel:WORD_1 src1_sel:DWORD
	v_add3_u32 v6, v1, v6, s33
	v_add_f32_e32 v0, 1.0, v0
	v_rcp_f32_e32 v19, v0
	s_nop 0
	v_pk_mul_f32 v[0:1], v[18:19], v[2:3]
	s_nop 0
	v_pk_mul_f32 v[0:1], v[4:5], v[0:1]
	v_mov_b32_e32 v5, v10
	v_and_b32_sdwa v2, v1, v229 dst_sel:DWORD dst_unused:UNUSED_PAD src0_sel:WORD_1 src1_sel:DWORD
	v_add3_u32 v1, v1, v2, s33
	v_and_b32_e32 v2, 0xffff0000, v38
	v_mov_b32_e32 v10, v9
	v_mul_f32_e32 v9, 0xbfb8aa3b, v2
	v_and_b32_sdwa v3, v0, v229 dst_sel:DWORD dst_unused:UNUSED_PAD src0_sel:WORD_1 src1_sel:DWORD
	v_exp_f32_e32 v9, v9
	v_add3_u32 v0, v0, v3, s33
	v_and_b32_e32 v1, 0xffff0000, v1
	v_and_b32_e32 v0, 0xffff0000, v0
	v_or_b32_sdwa v1, v1, v6 dst_sel:DWORD dst_unused:UNUSED_PAD src0_sel:DWORD src1_sel:WORD_1
	v_or_b32_sdwa v0, v0, v7 dst_sel:DWORD dst_unused:UNUSED_PAD src0_sel:DWORD src1_sel:WORD_1
	global_store_dwordx2 v[34:35], v[0:1], off offset:80
	v_lshlrev_b32_e32 v1, 16, v39
	v_lshlrev_b32_e32 v0, 16, v38
	v_add_f32_e32 v9, 1.0, v9
	v_mov_b32_e32 v4, v8
	v_pk_mul_f32 v[6:7], v[10:11], v[32:33] op_sel_hi:[1,0]
	v_mul_f32_e32 v8, 0xbfb8aa3b, v0
	v_rcp_f32_e32 v10, v9
	v_mul_f32_e32 v9, 0xbfb8aa3b, v1
	v_exp_f32_e32 v8, v8
	v_exp_f32_e32 v9, v9
	v_pk_mul_f32 v[4:5], v[4:5], v[32:33] op_sel_hi:[1,0]
	v_and_b32_e32 v3, 0xffff0000, v39
	v_add_f32_e32 v8, 1.0, v8
	v_add_f32_e32 v9, 1.0, v9
	v_rcp_f32_e32 v8, v8
	v_rcp_f32_e32 v9, v9
	s_nop 0
	v_pk_mul_f32 v[0:1], v[8:9], v[0:1]
	s_nop 0
	v_pk_mul_f32 v[0:1], v[4:5], v[0:1]
	s_nop 0
	v_and_b32_sdwa v5, v0, v229 dst_sel:DWORD dst_unused:UNUSED_PAD src0_sel:WORD_1 src1_sel:DWORD
	v_add3_u32 v5, v0, v5, s33
	v_mul_f32_e32 v0, 0xbfb8aa3b, v3
	v_exp_f32_e32 v0, v0
	v_and_b32_sdwa v4, v1, v229 dst_sel:DWORD dst_unused:UNUSED_PAD src0_sel:WORD_1 src1_sel:DWORD
	v_add3_u32 v4, v1, v4, s33
	v_add_f32_e32 v0, 1.0, v0
	v_rcp_f32_e32 v11, v0
	s_nop 0
	v_pk_mul_f32 v[0:1], v[10:11], v[2:3]
	s_nop 0
	v_pk_mul_f32 v[0:1], v[6:7], v[0:1]
	s_nop 0
	v_and_b32_sdwa v2, v1, v229 dst_sel:DWORD dst_unused:UNUSED_PAD src0_sel:WORD_1 src1_sel:DWORD
	v_add3_u32 v1, v1, v2, s33
	v_and_b32_e32 v2, 0xffff0000, v36
	v_mul_f32_e32 v9, 0xbfb8aa3b, v2
	v_exp_f32_e32 v9, v9
	v_and_b32_sdwa v3, v0, v229 dst_sel:DWORD dst_unused:UNUSED_PAD src0_sel:WORD_1 src1_sel:DWORD
	v_add3_u32 v0, v0, v3, s33
	v_and_b32_e32 v1, 0xffff0000, v1
	v_and_b32_e32 v0, 0xffff0000, v0
	v_or_b32_sdwa v1, v1, v4 dst_sel:DWORD dst_unused:UNUSED_PAD src0_sel:DWORD src1_sel:WORD_1
	v_or_b32_sdwa v0, v0, v5 dst_sel:DWORD dst_unused:UNUSED_PAD src0_sel:DWORD src1_sel:WORD_1
	v_lshlrev_b32_e32 v5, 16, v37
	v_lshlrev_b32_e32 v4, 16, v36
	v_add_f32_e32 v9, 1.0, v9
	v_mul_f32_e32 v8, 0xbfb8aa3b, v4
	v_rcp_f32_e32 v10, v9
	v_mul_f32_e32 v9, 0xbfb8aa3b, v5
	v_exp_f32_e32 v8, v8
	v_exp_f32_e32 v9, v9
	global_store_dwordx2 v[34:35], v[0:1], off offset:96
	v_mov_b32_e32 v0, v12
	v_add_f32_e32 v8, 1.0, v8
	v_add_f32_e32 v9, 1.0, v9
	v_rcp_f32_e32 v8, v8
	v_rcp_f32_e32 v9, v9
	v_mov_b32_e32 v1, v14
	v_pk_mul_f32 v[0:1], v[0:1], v[32:33] op_sel_hi:[1,0]
	v_and_b32_e32 v3, 0xffff0000, v37
	v_pk_mul_f32 v[4:5], v[8:9], v[4:5]
	v_mov_b32_e32 v14, v13
	v_pk_mul_f32 v[0:1], v[0:1], v[4:5]
	v_pk_mul_f32 v[6:7], v[14:15], v[32:33] op_sel_hi:[1,0]
	v_and_b32_sdwa v5, v0, v229 dst_sel:DWORD dst_unused:UNUSED_PAD src0_sel:WORD_1 src1_sel:DWORD
	v_add3_u32 v5, v0, v5, s33
	v_mul_f32_e32 v0, 0xbfb8aa3b, v3
	v_exp_f32_e32 v0, v0
	v_and_b32_sdwa v4, v1, v229 dst_sel:DWORD dst_unused:UNUSED_PAD src0_sel:WORD_1 src1_sel:DWORD
	v_add3_u32 v4, v1, v4, s33
	v_add_f32_e32 v0, 1.0, v0
	v_rcp_f32_e32 v11, v0
	s_nop 0
	v_pk_mul_f32 v[0:1], v[10:11], v[2:3]
	s_nop 0
	v_pk_mul_f32 v[0:1], v[6:7], v[0:1]
	s_nop 0
	v_and_b32_sdwa v2, v1, v229 dst_sel:DWORD dst_unused:UNUSED_PAD src0_sel:WORD_1 src1_sel:DWORD
	v_and_b32_sdwa v3, v0, v229 dst_sel:DWORD dst_unused:UNUSED_PAD src0_sel:WORD_1 src1_sel:DWORD
	v_add3_u32 v1, v1, v2, s33
	v_add3_u32 v0, v0, v3, s33
	v_and_b32_e32 v1, 0xffff0000, v1
	v_and_b32_e32 v0, 0xffff0000, v0
	v_or_b32_sdwa v1, v1, v4 dst_sel:DWORD dst_unused:UNUSED_PAD src0_sel:DWORD src1_sel:WORD_1
	v_or_b32_sdwa v0, v0, v5 dst_sel:DWORD dst_unused:UNUSED_PAD src0_sel:DWORD src1_sel:WORD_1
	global_store_dwordx2 v[34:35], v[0:1], off offset:112
	s_cbranch_scc1 .LBB0_576
